# opt21: GEMM prologue requests K-tile 1's six DMA pieces right behind K-tile 0's eight (one cold round trip instead of two); on v049 stack
# baseline (speedup 1.0000x reference)
.LBB0_203:
	v_lshrrev_b32_e32 v2, 1, v128
	v_and_b32_e32 v132, 24, v2
	v_lshrrev_b32_e32 v2, 5, v128
	v_and_b32_e32 v2, 4, v2
	v_bfe_u32 v3, v128, 2, 2
	v_lshlrev_b32_e32 v0, 4, v128
	v_and_b32_e32 v1, 32, v128
	v_bfe_u32 v11, v128, 2, 4
	v_or3_b32 v2, v2, v3, v132
	v_lshrrev_b32_e32 v3, 3, v128
	s_movk_i32 s1, 0x70
	v_bitop3_b32 v9, v0, v1, 48 bitop3:0x6c
	v_and_b32_e32 v10, 64, v128
	v_and_or_b32 v4, v3, s1, v11
	s_movk_i32 s1, 0x60
	v_add_u32_e32 v12, 0x2000, v0
	s_lshr_b32 s5, s8, 6
	s_lshr_b32 s4, s8, 8
	v_or_b32_e32 v1, v9, v10
	v_and_or_b32 v3, v3, s1, v2
	v_lshrrev_b32_e32 v0, 7, v12
	s_movk_i32 s1, 0xf0
	s_lshl_b32 s58, s5, 10
	v_lshl_or_b32 v136, v3, 11, v1
	v_and_or_b32 v3, v0, s1, v11
	s_movk_i32 s1, 0xe0
	s_add_u32 s59, s70, 0x100000
	v_and_or_b32 v0, v0, s1, v2
	s_addc_u32 s62, s71, 0
	s_ashr_i32 s7, s6, 31
	s_ashr_i32 s1, s0, 31
	s_lshl_b64 s[10:11], s[6:7], 19
	s_lshl_b64 s[12:13], s[0:1], 19
	s_add_u32 s52, s59, s12
	s_addc_u32 s53, s62, s13
	s_add_i32 s63, s58, 0
	s_add_i32 m0, s63, 0x10000
	v_lshl_or_b32 v140, v0, 11, v1
	global_load_lds_dwordx4 v136, s[52:53]
	s_add_i32 m0, s63, 0x12000
	s_add_u32 s12, s52, 0x40000
	global_load_lds_dwordx4 v140, s[52:53]
	s_addc_u32 s13, s53, 0
	s_add_i32 m0, s63, 0x14000
	v_lshl_or_b32 v134, v4, 11, v1
	global_load_lds_dwordx4 v136, s[12:13]
	s_add_i32 m0, s63, 0x16000
	s_add_u32 s50, s14, s10
	s_addc_u32 s51, s15, s11
	s_add_i32 s64, s63, 0x2000
	global_load_lds_dwordx4 v140, s[12:13]
	s_mov_b32 m0, s63
	s_add_u32 s10, s50, 0x40000
	v_lshl_or_b32 v138, v3, 11, v1
	global_load_lds_dwordx4 v134, s[50:51]
	s_mov_b32 m0, s64
	s_addc_u32 s11, s51, 0
	s_add_i32 s65, s63, 0x4000
	global_load_lds_dwordx4 v138, s[50:51]
	s_mov_b32 m0, s65
	s_add_i32 s66, s63, 0x6000
	global_load_lds_dwordx4 v134, s[10:11]
	s_mov_b32 m0, s66
	v_mov_b32_e32 v143, 0
	global_load_lds_dwordx4 v138, s[10:11]
	v_mov_b32_e32 v137, v143
	v_mov_b32_e32 v141, v143
	v_mov_b32_e32 v135, v143
	v_mov_b32_e32 v139, v143
	s_cmp_eq_u32 s4, 1
	s_mov_b32 s9, 0
	v_lshl_add_u64 v[6:7], s[52:53], 0, v[136:137]
	v_lshl_add_u64 v[4:5], s[52:53], 0, v[140:141]
	v_lshl_add_u64 v[0:1], s[50:51], 0, v[134:135]
	s_cselect_b64 s[10:11], -1, 0
	v_lshl_add_u64 v[2:3], s[50:51], 0, v[138:139]
	s_add_u32 s20, s70, 0x13700000
	s_addc_u32 s21, s71, 0
	s_lshl_b32 s5, s5, 5
	s_mov_b64 s[22:23], 0x80
	s_and_b32 s67, s5, 0x60
	s_add_i32 m0, s63, 0x18000
	v_lshl_add_u64 v[6:7], v[6:7], 0, s[22:23]
	s_lshl_b32 s1, s4, 13
	s_lshl_b32 s5, s67, 7
	global_load_lds_dwordx4 v[6:7], off
	v_lshl_add_u64 v[4:5], v[4:5], 0, s[22:23]
	s_add_i32 m0, s63, 0x1a000
	s_add_i32 s79, s63, 0x8000
	s_add_i32 s81, s63, 0xa000
	global_load_lds_dwordx4 v[4:5], off
	v_lshl_add_u64 v[0:1], v[0:1], 0, s[22:23]
	s_mov_b32 m0, s79
	s_add_u32 s12, s52, 0x40080
	global_load_lds_dwordx4 v[0:1], off
	v_lshl_add_u64 v[0:1], v[2:3], 0, s[22:23]
	s_mov_b32 m0, s81
	s_addc_u32 s13, s53, 0
	global_load_lds_dwordx4 v[0:1], off
	s_add_i32 m0, s63, 0x1c000
	v_lshl_add_u64 v[0:1], s[12:13], 0, v[136:137]
	global_load_lds_dwordx4 v[0:1], off
	v_lshl_add_u64 v[0:1], s[12:13], 0, v[140:141]
	s_add_i32 m0, s63, 0x1e000
	global_load_lds_dwordx4 v[0:1], off
	s_cmp_lg_u32 s4, 1
	s_cbranch_scc1 .LBB0_205
	s_barrier
.LBB0_205:
	s_waitcnt vmcnt(8)
	s_barrier
	s_cmpk_lt_u32 s8, 0x100
	v_and_b32_e32 v0, 15, v128
	v_lshlrev_b32_e32 v1, 1, v132
	v_lshl_or_b32 v131, s4, 6, v0
	v_lshl_or_b32 v2, v0, 6, v1
	v_lshlrev_b32_e32 v0, 2, v0
	v_and_b32_e32 v3, 32, v0
	v_bitop3_b32 v2, v2, s1, v3 bitop3:0xde
	v_lshlrev_b32_e32 v3, 6, v128
	s_movk_i32 s1, 0x3c0
	v_and_or_b32 v1, v3, s1, v1
	s_cselect_b64 s[26:27], -1, 0
	s_lshl_b32 s1, s4, 8
	s_add_i32 s1, s1, 0
	s_add_i32 s1, s1, 0x20000
	v_and_b32_e32 v3, 32, v8
	v_add_u32_e32 v156, s1, v0
	v_lshlrev_b32_e32 v0, 8, v128
	v_bitop3_b32 v133, s5, v1, v3 bitop3:0xf6
	v_and_b32_e32 v0, 0x38000, v0
	v_lshlrev_b32_e32 v1, 11, v11
	v_or3_b32 v0, v9, v0, v1
	v_add_u32_e32 v144, v0, v10
	v_lshlrev_b32_e32 v0, 4, v12
	s_waitcnt vmcnt(6)
	v_and_b32_e32 v0, 0x78000, v0
	v_or3_b32 v0, v9, v0, v1
	s_add_i32 s82, 0, 0x10000
	s_add_i32 s83, 0, 0x14000
	v_mov_b32_e32 v145, v143
	v_add_u32_e32 v146, v0, v10
	v_mov_b32_e32 v147, v143
	v_mov_b64_e32 v[148:149], 0x600
	v_mov_b64_e32 v[150:151], 0x5ff
	s_movk_i32 s77, 0xc1
	v_add_u32_e32 v157, s82, v133
	v_add_u32_e32 v158, s83, v133
	v_add_u32_e32 v159, 0, v2
	s_mov_b32 s1, 0
	s_mov_b32 s84, 0
	s_barrier
	s_branch .LBB0_208

.LBB0_374:
	v_lshrrev_b32_e32 v2, 1, v128
	v_lshrrev_b32_e32 v3, 5, v128
	v_and_b32_e32 v2, 24, v2
	v_and_b32_e32 v3, 4, v3
	v_bfe_u32 v4, v128, 2, 2
	v_lshlrev_b32_e32 v0, 4, v128
	v_and_b32_e32 v1, 32, v128
	v_bfe_u32 v10, v128, 2, 4
	v_or3_b32 v2, v3, v4, v2
	v_lshrrev_b32_e32 v3, 3, v128
	s_movk_i32 s1, 0x70
	v_bitop3_b32 v8, v0, v1, 48 bitop3:0x6c
	v_and_b32_e32 v9, 64, v128
	v_and_or_b32 v4, v3, s1, v10
	s_movk_i32 s1, 0x60
	v_add_u32_e32 v11, 0x2000, v0
	v_or_b32_e32 v1, v8, v9
	v_and_or_b32 v3, v3, s1, v2
	v_lshrrev_b32_e32 v0, 7, v11
	s_movk_i32 s1, 0xf0
	s_add_u32 s3, s70, 0x700000
	v_lshl_or_b32 v134, v3, 11, v1
	v_and_or_b32 v3, v0, s1, v10
	s_movk_i32 s1, 0xe0
	s_addc_u32 s56, s71, 0
	s_lshr_b32 s5, s6, 6
	v_and_or_b32 v0, v0, s1, v2
	s_ashr_i32 s49, s48, 31
	s_ashr_i32 s1, s0, 31
	s_lshr_b32 s4, s6, 8
	s_lshl_b32 s57, s5, 10
	s_lshl_b64 s[8:9], s[48:49], 19
	s_lshl_b64 s[10:11], s[0:1], 19
	s_add_u32 s52, s3, s10
	s_addc_u32 s53, s56, s11
	s_add_i32 s58, s57, 0
	s_add_i32 m0, s58, 0x10000
	v_lshl_or_b32 v138, v0, 11, v1
	global_load_lds_dwordx4 v134, s[52:53]
	s_add_i32 m0, s58, 0x12000
	s_add_u32 s10, s52, 0x40000
	global_load_lds_dwordx4 v138, s[52:53]
	s_addc_u32 s11, s53, 0
	s_add_i32 m0, s58, 0x14000
	v_lshl_or_b32 v132, v4, 11, v1
	global_load_lds_dwordx4 v134, s[10:11]
	s_add_i32 m0, s58, 0x16000
	s_add_u32 s50, s20, s8
	s_addc_u32 s51, s21, s9
	s_add_i32 s59, s58, 0x2000
	global_load_lds_dwordx4 v138, s[10:11]
	s_mov_b32 m0, s58
	s_add_u32 s8, s50, 0x40000
	v_lshl_or_b32 v136, v3, 11, v1
	global_load_lds_dwordx4 v132, s[50:51]
	s_mov_b32 m0, s59
	s_addc_u32 s9, s51, 0
	s_add_i32 s62, s58, 0x4000
	global_load_lds_dwordx4 v136, s[50:51]
	s_mov_b32 m0, s62
	s_add_i32 s63, s58, 0x6000
	global_load_lds_dwordx4 v132, s[8:9]
	s_mov_b32 m0, s63
	v_mov_b32_e32 v135, 0
	global_load_lds_dwordx4 v136, s[8:9]
	v_mov_b32_e32 v139, v135
	v_mov_b32_e32 v133, v135
	v_mov_b32_e32 v137, v135
	s_cmp_eq_u32 s4, 1
	s_mov_b32 s1, 0
	v_lshl_add_u64 v[6:7], s[52:53], 0, v[134:135]
	v_lshl_add_u64 v[4:5], s[52:53], 0, v[138:139]
	v_lshl_add_u64 v[0:1], s[50:51], 0, v[132:133]
	s_cselect_b64 s[8:9], -1, 0
	v_lshl_add_u64 v[2:3], s[50:51], 0, v[136:137]
	s_mov_b64 s[10:11], 0x80
	s_and_b32 s64, s5, 3
	s_add_i32 m0, s58, 0x18000
	v_lshl_add_u64 v[6:7], v[6:7], 0, s[10:11]
	s_lshl_b32 s5, s4, 13
	s_lshl_b32 s7, s64, 12
	global_load_lds_dwordx4 v[6:7], off
	v_lshl_add_u64 v[4:5], v[4:5], 0, s[10:11]
	s_add_i32 m0, s58, 0x1a000
	s_add_i32 s65, s58, 0x8000
	s_add_i32 s66, s58, 0xa000
	global_load_lds_dwordx4 v[4:5], off
	v_lshl_add_u64 v[0:1], v[0:1], 0, s[10:11]
	s_mov_b32 m0, s65
	s_add_u32 s12, s52, 0x40080
	global_load_lds_dwordx4 v[0:1], off
	v_lshl_add_u64 v[0:1], v[2:3], 0, s[10:11]
	s_mov_b32 m0, s66
	s_addc_u32 s13, s53, 0
	global_load_lds_dwordx4 v[0:1], off
	s_add_i32 m0, s58, 0x1c000
	v_lshl_add_u64 v[0:1], s[12:13], 0, v[134:135]
	global_load_lds_dwordx4 v[0:1], off
	v_lshl_add_u64 v[0:1], s[12:13], 0, v[138:139]
	s_add_i32 m0, s58, 0x1e000
	v_lshlrev_b32_e32 v4, 2, v128
	global_load_lds_dwordx4 v[0:1], off
	s_cmp_lg_u32 s4, 1
	s_cbranch_scc1 .LBB0_376
	s_barrier
.LBB0_376:
	s_waitcnt vmcnt(8)
	s_barrier
	v_bfe_u32 v0, v128, 4, 2
	v_and_b32_e32 v1, 15, v128
	v_lshlrev_b32_e32 v3, 4, v0
	v_lshl_or_b32 v131, s4, 6, v1
	v_lshl_or_b32 v1, v1, 6, v3
	v_and_b32_e32 v4, 32, v4
	v_lshlrev_b32_e32 v5, 6, v128
	s_movk_i32 s4, 0x3c0
	v_lshlrev_b32_e32 v2, 3, v0
	v_bitop3_b32 v1, v1, s5, v4 bitop3:0xde
	v_and_or_b32 v3, v5, s4, v3
	v_cmp_eq_u32_e64 s[4:5], 0, v0
	v_lshlrev_b32_e32 v0, 8, v128
	v_lshl_or_b32 v153, s64, 5, v2
	v_and_b32_e32 v0, 0x38000, v0
	v_lshlrev_b32_e32 v2, 11, v10
	v_or3_b32 v0, v8, v0, v2
	v_add_u32_e32 v140, v0, v9
	v_lshlrev_b32_e32 v0, 4, v11
	v_and_b32_e32 v0, 0x78000, v0
	s_waitcnt vmcnt(6)
	s_cmpk_lt_u32 s6, 0x100
	v_or3_b32 v0, v8, v0, v2
	v_bitop3_b32 v152, s7, v3, v4 bitop3:0xf6
	s_cselect_b64 s[22:23], -1, 0
	v_add_u32_e32 v142, v0, v9
	s_add_i32 s82, 0, 0x10000
	s_add_i32 s83, 0, 0x14000
	v_mbcnt_lo_u32_b32 v0, -1, 0
	s_ashr_i32 s67, s72, 31
	s_mov_b32 s79, s72
	s_ashr_i32 s81, s2, 31
	v_mov_b32_e32 v141, v135
	v_mov_b32_e32 v143, v135
	v_mov_b64_e32 v[144:145], 0x200
	v_mov_b64_e32 v[146:147], 0x1ff
	v_add_u32_e32 v154, s82, v152
	s_waitcnt lgkmcnt(0)
	v_add_u32_e32 v155, s83, v152
	v_add_u32_e32 v157, 0, v1
	v_mbcnt_hi_u32_b32 v158, -1, v0
	s_mov_b32 s84, 0
	s_barrier
	s_branch .LBB0_379

.LBB0_467:
	s_or_b64 exec, exec, s[0:1]
	s_cmpk_gt_i32 s2, 0xaff
	v_readfirstlane_b32 s5, v128
	s_waitcnt vmcnt(0) lgkmcnt(0)
	s_barrier
	s_cbranch_scc1 .LBB0_483
	v_lshrrev_b32_e32 v0, 5, v128
	v_lshrrev_b32_e32 v2, 1, v128
	v_and_b32_e32 v0, 4, v0
	v_bfe_u32 v1, v128, 2, 2
	v_and_b32_e32 v12, 24, v2
	v_or3_b32 v0, v0, v1, v12
	v_lshlrev_b32_e32 v1, 4, v128
	v_add_u32_e32 v9, 0x2000, v1
	v_lshrrev_b32_e32 v2, 7, v9
	s_movk_i32 s0, 0xe0
	v_and_b32_e32 v4, 32, v128
	v_and_or_b32 v3, v2, s0, v0
	v_bitop3_b32 v10, v1, v4, 48 bitop3:0x6c
	v_and_b32_e32 v11, 64, v128
	v_bfe_u32 v13, v128, 2, 4
	s_movk_i32 s0, 0xf0
	s_lshr_b32 s6, s5, 6
	v_or_b32_e32 v1, v10, v11
	v_and_or_b32 v2, v2, s0, v13
	s_lshr_b32 s10, s5, 8
	s_lshl_b32 s54, s6, 10
	v_lshl_or_b32 v134, v2, 11, v1
	v_lshrrev_b32_e32 v2, 3, v128
	s_movk_i32 s0, 0x60
	s_add_u32 s55, s70, 0x900000
	v_and_or_b32 v0, v2, s0, v0
	s_movk_i32 s0, 0x70
	s_addc_u32 s56, s71, 0
	v_lshl_or_b32 v136, v0, 11, v1
	v_and_or_b32 v0, v2, s0, v13
	s_lshr_b32 s0, s3, 29
	s_add_i32 s0, s2, s0
	s_ashr_i32 s1, s0, 3
	s_and_b32 s0, s0, -8
	s_sub_i32 s0, s2, s0
	s_cmp_lt_i32 s0, 0
	s_movk_i32 s57, 0x161
	s_cselect_b32 s4, s57, 0x160
	s_mul_i32 s0, s0, s4
	s_add_i32 s0, s0, s1
	s_mul_hi_i32 s1, s0, 0x2e8ba2e9
	s_lshr_b32 s4, s1, 31
	s_ashr_i32 s1, s1, 5
	s_add_i32 s1, s1, s4
	s_lshl_b32 s7, s1, 3
	s_mulk_i32 s1, 0xb0
	s_sub_i32 s0, s0, s1
	s_bfe_u32 s1, s0, 0x3001c
	s_add_i32 s1, s0, s1
	s_sext_i32_i16 s4, s1
	s_and_b32 s1, s1, 0xfff8
	s_sub_i32 s0, s0, s1
	s_sext_i32_i16 s0, s0
	s_lshr_b32 s4, s4, 3
	s_add_i32 s40, s7, s0
	s_ashr_i32 s41, s40, 31
	s_bfe_i64 s[8:9], s[4:5], 0x100000
	s_lshl_b64 s[0:1], s[40:41], 19
	s_lshl_b64 s[8:9], s[8:9], 19
	s_add_u32 s48, s55, s8
	s_addc_u32 s49, s56, s9
	s_add_i32 s41, s54, 0
	s_add_i32 m0, s41, 0x10000
	v_lshl_or_b32 v132, v3, 11, v1
	global_load_lds_dwordx4 v136, s[48:49]
	s_add_i32 m0, s41, 0x12000
	s_add_u32 s8, s48, 0x40000
	global_load_lds_dwordx4 v132, s[48:49]
	s_addc_u32 s9, s49, 0
	s_add_i32 m0, s41, 0x14000
	v_lshl_or_b32 v138, v0, 11, v1
	global_load_lds_dwordx4 v136, s[8:9]
	s_add_i32 m0, s41, 0x16000
	s_add_u32 s42, s14, s0
	s_addc_u32 s43, s15, s1
	s_add_i32 s58, s41, 0x2000
	global_load_lds_dwordx4 v132, s[8:9]
	s_mov_b32 m0, s41
	s_add_u32 s0, s42, 0x40000
	global_load_lds_dwordx4 v138, s[42:43]
	s_mov_b32 m0, s58
	s_addc_u32 s1, s43, 0
	s_add_i32 s59, s41, 0x4000
	global_load_lds_dwordx4 v134, s[42:43]
	s_mov_b32 m0, s59
	s_add_i32 s62, s41, 0x6000
	global_load_lds_dwordx4 v138, s[0:1]
	s_mov_b32 m0, s62
	v_mov_b32_e32 v137, 0
	global_load_lds_dwordx4 v134, s[0:1]
	v_mov_b32_e32 v133, v137
	v_mov_b32_e32 v139, v137
	v_mov_b32_e32 v135, v137
	s_cmp_eq_u32 s10, 1
	s_mov_b32 s12, 0
	v_lshl_add_u64 v[6:7], s[48:49], 0, v[136:137]
	v_lshl_add_u64 v[4:5], s[48:49], 0, v[132:133]
	v_lshl_add_u64 v[0:1], s[42:43], 0, v[138:139]
	s_cselect_b64 s[0:1], -1, 0
	v_lshl_add_u64 v[2:3], s[42:43], 0, v[134:135]
	s_lshl_b32 s6, s6, 5
	s_and_b32 s22, s6, 0x60
	s_mov_b64 s[6:7], 0x80
	s_add_i32 m0, s41, 0x18000
	v_lshl_add_u64 v[6:7], v[6:7], 0, s[6:7]
	s_lshl_b32 s11, s10, 13
	s_lshl_b32 s23, s22, 7
	global_load_lds_dwordx4 v[6:7], off
	v_lshl_add_u64 v[4:5], v[4:5], 0, s[6:7]
	s_add_i32 m0, s41, 0x1a000
	s_add_i32 s63, s41, 0x8000
	s_add_i32 s64, s41, 0xa000
	global_load_lds_dwordx4 v[4:5], off
	v_lshl_add_u64 v[0:1], v[0:1], 0, s[6:7]
	s_mov_b32 m0, s63
	s_add_u32 s8, s48, 0x40080
	global_load_lds_dwordx4 v[0:1], off
	v_lshl_add_u64 v[0:1], v[2:3], 0, s[6:7]
	s_mov_b32 m0, s64
	s_addc_u32 s9, s49, 0
	global_load_lds_dwordx4 v[0:1], off
	s_add_i32 m0, s41, 0x1c000
	v_lshl_add_u64 v[0:1], s[8:9], 0, v[136:137]
	global_load_lds_dwordx4 v[0:1], off
	v_lshl_add_u64 v[0:1], s[8:9], 0, v[132:133]
	s_add_i32 m0, s41, 0x1e000
	s_sext_i32_i16 s13, s4
	global_load_lds_dwordx4 v[0:1], off
	s_cmp_lg_u32 s10, 1
	s_cbranch_scc1 .LBB0_470
	s_barrier
.LBB0_470:
	s_waitcnt vmcnt(8)
	s_barrier
	v_and_b32_e32 v0, 15, v128
	v_lshlrev_b32_e32 v1, 1, v12
	v_lshl_or_b32 v131, s10, 6, v0
	v_lshl_or_b32 v2, v0, 6, v1
	v_lshlrev_b32_e32 v0, 2, v0
	v_and_b32_e32 v3, 32, v0
	v_bitop3_b32 v2, v2, s11, v3 bitop3:0xde
	v_lshlrev_b32_e32 v3, 6, v128
	s_movk_i32 s4, 0x3c0
	s_cmpk_lt_u32 s5, 0x100
	v_and_or_b32 v1, v3, s4, v1
	s_cselect_b64 s[8:9], -1, 0
	s_lshl_b32 s4, s10, 8
	s_add_i32 s4, s4, 0
	s_add_i32 s4, s4, 0x20000
	v_and_b32_e32 v3, 32, v8
	v_add_u32_e32 v153, s4, v0
	v_lshlrev_b32_e32 v0, 8, v128
	v_bitop3_b32 v152, s23, v1, v3 bitop3:0xf6
	v_and_b32_e32 v0, 0x38000, v0
	v_lshlrev_b32_e32 v1, 11, v13
	v_or3_b32 v0, v10, v0, v1
	v_add_u32_e32 v140, v0, v11
	v_lshlrev_b32_e32 v0, 4, v9
	s_waitcnt vmcnt(6)
	v_and_b32_e32 v0, 0x78000, v0
	v_or3_b32 v0, v10, v0, v1
	s_add_i32 s65, 0, 0x10000
	s_add_i32 s66, 0, 0x14000
	v_or_b32_e32 v154, s22, v12
	v_mov_b32_e32 v141, v137
	v_add_u32_e32 v142, v0, v11
	v_mov_b32_e32 v143, v137
	v_mov_b64_e32 v[144:145], 0xb00
	v_mov_b64_e32 v[146:147], 0xaff
	v_add_u32_e32 v155, s65, v152
	v_add_u32_e32 v157, s66, v152
	v_add_u32_e32 v158, 0, v2
	s_movk_i32 s67, 0x1600
	s_mov_b32 s77, 0
	s_barrier
	s_branch .LBB0_473

.LBB0_546:
	v_lshrrev_b32_e32 v3, 1, v128
	v_lshrrev_b32_e32 v4, 5, v128
	v_and_b32_e32 v3, 24, v3
	v_and_b32_e32 v4, 4, v4
	v_bfe_u32 v5, v128, 2, 2
	v_lshlrev_b32_e32 v0, 4, v128
	s_waitcnt lgkmcnt(0)
	v_and_b32_e32 v1, 32, v128
	v_bfe_u32 v2, v128, 2, 4
	v_or3_b32 v3, v4, v5, v3
	v_lshrrev_b32_e32 v4, 3, v128
	s_movk_i32 s0, 0x70
	v_bitop3_b32 v8, v0, v1, 48 bitop3:0x6c
	v_and_or_b32 v5, v4, s0, v2
	s_movk_i32 s0, 0x60
	v_add_u32_e32 v0, 0x2000, v0
	s_add_u32 s3, s70, 0x1400000
	v_and_or_b32 v4, v4, s0, v3
	v_lshrrev_b32_e32 v0, 7, v0
	s_movk_i32 s0, 0xf0
	s_addc_u32 s50, s71, 0
	s_lshr_b32 s1, s6, 6
	v_and_b32_e32 v9, 64, v128
	v_and_or_b32 v2, v0, s0, v2
	s_movk_i32 s0, 0xe0
	v_or_b32_e32 v1, v8, v9
	v_and_or_b32 v0, v0, s0, v3
	s_lshr_b32 s0, s6, 8
	s_lshl_b32 s51, s1, 10
	s_mul_i32 s5, s8, 0x160000
	v_lshrrev_b32_e32 v1, 1, v1
	v_mul_u32_u24_e32 v4, 0xb00, v4
	s_mul_hi_i32 s4, s8, 0x160000
	s_add_u32 s42, s3, s5
	v_or_b32_e32 v4, v4, v1
	s_addc_u32 s43, s50, s4
	s_add_i32 s52, s51, 0
	v_lshlrev_b32_e32 v134, 1, v4
	v_mul_u32_u24_e32 v0, 0xb00, v0
	s_add_i32 m0, s52, 0x10000
	v_or_b32_e32 v0, v0, v1
	global_load_lds_dwordx4 v134, s[42:43]
	s_add_i32 m0, s52, 0x12000
	v_lshlrev_b32_e32 v138, 1, v0
	s_add_u32 s4, s42, 0xb0000
	global_load_lds_dwordx4 v138, s[42:43]
	s_addc_u32 s5, s43, 0
	s_add_i32 m0, s52, 0x14000
	s_mul_i32 s9, s12, 0x160000
	global_load_lds_dwordx4 v134, s[4:5]
	s_add_i32 m0, s52, 0x16000
	v_mul_u32_u24_e32 v10, 0xb00, v5
	s_mul_hi_i32 s7, s12, 0x160000
	s_add_u32 s40, s16, s9
	v_or_b32_e32 v5, v1, v10
	v_mul_u32_u24_e32 v11, 0xb00, v2
	s_addc_u32 s41, s17, s7
	s_add_i32 s53, s52, 0x2000
	v_lshlrev_b32_e32 v132, 1, v5
	v_or_b32_e32 v2, v11, v1
	global_load_lds_dwordx4 v138, s[4:5]
	s_mov_b32 m0, s52
	s_add_u32 s4, s40, 0xb0000
	v_lshlrev_b32_e32 v136, 1, v2
	global_load_lds_dwordx4 v132, s[40:41]
	s_mov_b32 m0, s53
	s_addc_u32 s5, s41, 0
	s_add_i32 s54, s52, 0x4000
	global_load_lds_dwordx4 v136, s[40:41]
	s_mov_b32 m0, s54
	s_add_i32 s55, s52, 0x6000
	global_load_lds_dwordx4 v132, s[4:5]
	s_mov_b32 m0, s55
	v_mov_b32_e32 v135, 0
	global_load_lds_dwordx4 v136, s[4:5]
	v_mov_b32_e32 v139, v135
	v_mov_b32_e32 v133, v135
	v_mov_b32_e32 v137, v135
	s_cmp_eq_u32 s0, 1
	s_mov_b32 s9, 0
	v_lshl_add_u64 v[6:7], s[42:43], 0, v[134:135]
	v_lshl_add_u64 v[4:5], s[42:43], 0, v[138:139]
	v_lshl_add_u64 v[0:1], s[40:41], 0, v[132:133]
	s_cselect_b64 s[10:11], -1, 0
	v_lshl_add_u64 v[2:3], s[40:41], 0, v[136:137]
	s_mov_b64 s[22:23], 0x80
	s_and_b32 s56, s1, 3
	s_add_i32 m0, s52, 0x18000
	v_lshl_add_u64 v[6:7], v[6:7], 0, s[22:23]
	s_lshl_b32 s1, s0, 13
	s_lshl_b32 s7, s56, 12
	global_load_lds_dwordx4 v[6:7], off
	v_lshl_add_u64 v[4:5], v[4:5], 0, s[22:23]
	s_add_i32 m0, s52, 0x1a000
	s_add_i32 s57, s52, 0x8000
	s_add_i32 s58, s52, 0xa000
	global_load_lds_dwordx4 v[4:5], off
	v_lshl_add_u64 v[0:1], v[0:1], 0, s[22:23]
	s_mov_b32 m0, s57
	s_add_u32 s4, s42, 0xb0080
	global_load_lds_dwordx4 v[0:1], off
	v_lshl_add_u64 v[0:1], v[2:3], 0, s[22:23]
	s_mov_b32 m0, s58
	s_addc_u32 s5, s43, 0
	global_load_lds_dwordx4 v[0:1], off
	s_add_i32 m0, s52, 0x1c000
	v_lshl_add_u64 v[0:1], s[4:5], 0, v[134:135]
	global_load_lds_dwordx4 v[0:1], off
	v_lshl_add_u64 v[0:1], s[4:5], 0, v[138:139]
	s_add_i32 m0, s52, 0x1e000
	v_lshlrev_b32_e32 v4, 2, v128
	global_load_lds_dwordx4 v[0:1], off
	s_cmp_lg_u32 s0, 1
	s_cbranch_scc1 .LBB0_548
	s_barrier
.LBB0_548:
	s_waitcnt vmcnt(8)
	s_barrier
	v_bfe_u32 v0, v128, 4, 2
	v_and_b32_e32 v1, 15, v128
	v_lshl_or_b32 v131, s0, 6, v1
	v_lshlrev_b32_e32 v2, 3, v0
	v_lshlrev_b32_e32 v3, 4, v0
	v_lshlrev_b32_e32 v5, 6, v128
	s_movk_i32 s0, 0x3c0
	v_cmp_eq_u32_e64 s[4:5], 0, v0
	v_add_u16_e32 v0, v8, v9
	v_lshl_or_b32 v1, v1, 6, v3
	v_and_b32_e32 v4, 32, v4
	v_and_or_b32 v3, v5, s0, v3
	s_waitcnt vmcnt(6)
	s_cmpk_lt_u32 s6, 0x100
	v_lshrrev_b16_e32 v0, 1, v0
	v_bitop3_b32 v1, v1, s1, v4 bitop3:0xde
	v_bitop3_b32 v152, s7, v3, v4 bitop3:0xf6
	s_cselect_b64 s[26:27], -1, 0
	v_add_lshl_u32 v140, v10, v0, 1
	v_add_lshl_u32 v142, v11, v0, 1
	s_add_i32 s64, 0, 0x10000
	s_add_i32 s65, 0, 0x14000
	v_mbcnt_lo_u32_b32 v0, -1, 0
	v_lshl_or_b32 v153, s56, 5, v2
	s_ashr_i32 s59, s72, 31
	s_mov_b32 s62, s72
	s_ashr_i32 s63, s2, 31
	v_mov_b32_e32 v141, v135
	v_mov_b32_e32 v143, v135
	v_mov_b64_e32 v[144:145], 0x200
	v_mov_b64_e32 v[146:147], 0x1ff
	v_add_u32_e32 v154, s64, v152
	v_add_u32_e32 v155, s65, v152
	v_add_u32_e32 v157, 0, v1
	v_mbcnt_hi_u32_b32 v158, -1, v0
	s_mov_b32 s66, 0
	s_barrier
	s_branch .LBB0_551

.LBB0_647:
	v_lshrrev_b32_e32 v2, 1, v128
	v_lshrrev_b32_e32 v3, 5, v128
	v_and_b32_e32 v2, 24, v2
	v_and_b32_e32 v3, 4, v3
	v_bfe_u32 v4, v128, 2, 2
	v_lshlrev_b32_e32 v0, 4, v128
	v_and_b32_e32 v1, 32, v128
	v_bfe_u32 v11, v128, 2, 4
	v_or3_b32 v2, v3, v4, v2
	v_lshrrev_b32_e32 v3, 3, v128
	s_movk_i32 s1, 0x70
	s_lshr_b32 s4, s6, 6
	v_bitop3_b32 v9, v0, v1, 48 bitop3:0x6c
	v_and_b32_e32 v10, 64, v128
	v_and_or_b32 v4, v3, s1, v11
	s_movk_i32 s1, 0x60
	v_add_u32_e32 v12, 0x2000, v0
	v_or_b32_e32 v1, v9, v10
	v_and_or_b32 v3, v3, s1, v2
	v_lshrrev_b32_e32 v0, 7, v12
	s_movk_i32 s1, 0xf0
	s_lshr_b32 s7, s6, 8
	s_lshl_b32 s62, s4, 10
	v_lshl_or_b32 v134, v3, 11, v1
	v_and_or_b32 v3, v0, s1, v11
	s_movk_i32 s1, 0xe0
	s_add_u32 s63, s70, 0x1980000
	v_and_or_b32 v0, v0, s1, v2
	s_addc_u32 s64, s71, 0
	s_ashr_i32 s9, s8, 31
	s_ashr_i32 s1, s0, 31
	s_lshl_b64 s[10:11], s[8:9], 19
	s_lshl_b64 s[12:13], s[0:1], 19
	s_add_u32 s54, s63, s12
	s_addc_u32 s55, s64, s13
	s_add_i32 s65, s62, 0
	s_add_i32 m0, s65, 0x10000
	v_lshl_or_b32 v138, v0, 11, v1
	global_load_lds_dwordx4 v134, s[54:55]
	s_add_i32 m0, s65, 0x12000
	s_add_u32 s12, s54, 0x40000
	global_load_lds_dwordx4 v138, s[54:55]
	s_addc_u32 s13, s55, 0
	s_add_i32 m0, s65, 0x14000
	v_lshl_or_b32 v132, v4, 11, v1
	global_load_lds_dwordx4 v134, s[12:13]
	s_add_i32 m0, s65, 0x16000
	s_add_u32 s52, s14, s10
	s_addc_u32 s53, s15, s11
	s_add_i32 s66, s65, 0x2000
	global_load_lds_dwordx4 v138, s[12:13]
	s_mov_b32 m0, s65
	s_add_u32 s10, s52, 0x40000
	v_lshl_or_b32 v136, v3, 11, v1
	global_load_lds_dwordx4 v132, s[52:53]
	s_mov_b32 m0, s66
	s_addc_u32 s11, s53, 0
	s_add_i32 s67, s65, 0x4000
	global_load_lds_dwordx4 v136, s[52:53]
	s_mov_b32 m0, s67
	s_add_i32 s79, s65, 0x6000
	global_load_lds_dwordx4 v132, s[10:11]
	s_mov_b32 m0, s79
	v_writelane_b32 v238, s94, 4
	global_load_lds_dwordx4 v136, s[10:11]
	v_mov_b32_e32 v135, 0
	v_writelane_b32 v238, s95, 5
	v_mov_b32_e32 v139, v135
	v_mov_b32_e32 v133, v135
	v_mov_b32_e32 v137, v135
	s_cmp_eq_u32 s7, 1
	v_writelane_b32 v238, s92, 6
	s_mov_b32 s11, 0
	v_lshl_add_u64 v[6:7], s[54:55], 0, v[134:135]
	v_lshl_add_u64 v[4:5], s[54:55], 0, v[138:139]
	v_lshl_add_u64 v[0:1], s[52:53], 0, v[132:133]
	s_cselect_b64 s[22:23], -1, 0
	v_lshl_add_u64 v[2:3], s[52:53], 0, v[136:137]
	v_writelane_b32 v238, s93, 7
	s_add_u32 s81, s70, 0x1f900000
	s_mov_b64 s[26:27], 0x80
	s_addc_u32 s82, s71, 0
	s_and_b32 s1, s4, 3
	s_add_i32 m0, s65, 0x18000
	v_lshl_add_u64 v[6:7], v[6:7], 0, s[26:27]
	s_lshl_b32 s9, s7, 13
	s_lshl_b32 s10, s1, 12
	global_load_lds_dwordx4 v[6:7], off
	v_lshl_add_u64 v[4:5], v[4:5], 0, s[26:27]
	s_add_i32 m0, s65, 0x1a000
	s_add_i32 s83, s65, 0x8000
	s_add_i32 s84, s65, 0xa000
	global_load_lds_dwordx4 v[4:5], off
	v_lshl_add_u64 v[0:1], v[0:1], 0, s[26:27]
	s_mov_b32 m0, s83
	s_add_u32 s4, s54, 0x40080
	global_load_lds_dwordx4 v[0:1], off
	v_lshl_add_u64 v[0:1], v[2:3], 0, s[26:27]
	s_mov_b32 m0, s84
	s_addc_u32 s5, s55, 0
	global_load_lds_dwordx4 v[0:1], off
	s_add_i32 m0, s65, 0x1c000
	v_lshl_add_u64 v[0:1], s[4:5], 0, v[134:135]
	global_load_lds_dwordx4 v[0:1], off
	v_lshl_add_u64 v[0:1], s[4:5], 0, v[138:139]
	s_add_i32 m0, s65, 0x1e000
	global_load_lds_dwordx4 v[0:1], off
	s_cmp_lg_u32 s7, 1
	s_cbranch_scc1 .LBB0_649
	s_barrier
.LBB0_649:
	s_waitcnt vmcnt(8)
	s_barrier
	s_cmpk_lt_u32 s6, 0x100
	v_bfe_u32 v1, v128, 4, 2
	v_and_b32_e32 v0, 15, v128
	v_lshlrev_b32_e32 v3, 4, v1
	s_cselect_b64 s[28:29], -1, 0
	s_lshl_b32 s6, s7, 8
	v_lshl_or_b32 v131, s7, 6, v0
	v_lshl_or_b32 v4, v0, 6, v3
	v_lshlrev_b32_e32 v0, 2, v0
	s_add_i32 s6, s6, 0
	v_and_b32_e32 v5, 32, v0
	s_add_i32 s6, s6, 0x20000
	v_bitop3_b32 v4, v4, s9, v5 bitop3:0xde
	v_lshlrev_b32_e32 v5, 6, v128
	s_movk_i32 s4, 0x3c0
	v_add_u32_e32 v159, s6, v0
	v_lshlrev_b32_e32 v0, 8, v128
	v_lshlrev_b32_e32 v2, 3, v1
	v_and_or_b32 v3, v5, s4, v3
	v_cmp_eq_u32_e64 s[4:5], 0, v1
	v_and_b32_e32 v0, 0x38000, v0
	v_lshlrev_b32_e32 v1, 11, v11
	v_or3_b32 v0, v9, v0, v1
	v_add_u32_e32 v140, v0, v10
	v_lshlrev_b32_e32 v0, 4, v12
	v_and_b32_e32 v0, 0x78000, v0
	v_and_b32_e32 v5, 32, v8
	s_waitcnt vmcnt(6)
	v_or3_b32 v0, v9, v0, v1
	v_bitop3_b32 v157, s10, v3, v5 bitop3:0xf6
	v_lshl_or_b32 v158, s1, 5, v2
	s_lshl_b32 s1, s1, 15
	v_add_u32_e32 v142, v0, v10
	s_add_i32 s88, 0, 0x10000
	s_add_i32 s89, 0, 0x14000
	v_mbcnt_lo_u32_b32 v0, -1, 0
	s_or_b32 s85, s1, 0xfff00000
	s_or_b32 s86, s1, 0xfff20000
	v_mov_b32_e32 v141, v135
	v_mov_b32_e32 v143, v135
	v_mov_b64_e32 v[144:145], 0x600
	v_mov_b64_e32 v[146:147], 0x5ff
	s_movk_i32 s87, 0xc1
	v_add_u32_e32 v160, s88, v157
	v_add_u32_e32 v161, s89, v157
	v_add_u32_e32 v162, 0, v4
	s_movk_i32 s92, 0x1800
	v_mbcnt_hi_u32_b32 v163, -1, v0
	s_mov_b32 s1, 0
	s_mov_b32 s93, 0
	s_barrier
	s_branch .LBB0_652

.LBB0_957:
	s_waitcnt vmcnt(0)
	v_lshrrev_b32_e32 v2, 1, v128
	v_lshrrev_b32_e32 v3, 5, v128
	v_and_b32_e32 v2, 24, v2
	v_and_b32_e32 v3, 4, v3
	v_bfe_u32 v4, v128, 2, 2
	v_lshlrev_b32_e32 v0, 4, v128
	s_waitcnt lgkmcnt(0)
	v_and_b32_e32 v1, 32, v128
	v_bfe_u32 v10, v128, 2, 4
	v_or3_b32 v2, v3, v4, v2
	v_lshrrev_b32_e32 v3, 3, v128
	s_movk_i32 s1, 0x70
	v_bitop3_b32 v8, v0, v1, 48 bitop3:0x6c
	v_and_b32_e32 v9, 64, v128
	v_and_or_b32 v4, v3, s1, v10
	s_movk_i32 s1, 0x60
	v_add_u32_e32 v11, 0x2000, v0
	v_or_b32_e32 v1, v8, v9
	v_and_or_b32 v3, v3, s1, v2
	v_lshrrev_b32_e32 v0, 7, v11
	s_movk_i32 s1, 0xf0
	s_add_u32 s3, s70, 0x1f80000
	v_lshl_or_b32 v134, v3, 11, v1
	v_and_or_b32 v3, v0, s1, v10
	s_movk_i32 s1, 0xe0
	s_addc_u32 s50, s71, 0
	s_lshr_b32 s5, s6, 6
	v_and_or_b32 v0, v0, s1, v2
	s_ashr_i32 s39, s38, 31
	s_ashr_i32 s1, s0, 31
	s_lshr_b32 s4, s6, 8
	s_lshl_b32 s51, s5, 10
	s_lshl_b64 s[8:9], s[38:39], 19
	s_lshl_b64 s[10:11], s[0:1], 19
	s_add_u32 s42, s3, s10
	s_addc_u32 s43, s50, s11
	s_add_i32 s52, s51, 0
	s_add_i32 m0, s52, 0x10000
	v_lshl_or_b32 v138, v0, 11, v1
	global_load_lds_dwordx4 v134, s[42:43]
	s_add_i32 m0, s52, 0x12000
	s_add_u32 s10, s42, 0x40000
	global_load_lds_dwordx4 v138, s[42:43]
	s_addc_u32 s11, s43, 0
	s_add_i32 m0, s52, 0x14000
	v_lshl_or_b32 v132, v4, 11, v1
	global_load_lds_dwordx4 v134, s[10:11]
	s_add_i32 m0, s52, 0x16000
	s_add_u32 s40, s20, s8
	s_addc_u32 s41, s21, s9
	s_add_i32 s53, s52, 0x2000
	global_load_lds_dwordx4 v138, s[10:11]
	s_mov_b32 m0, s52
	s_add_u32 s8, s40, 0x40000
	v_lshl_or_b32 v136, v3, 11, v1
	global_load_lds_dwordx4 v132, s[40:41]
	s_mov_b32 m0, s53
	s_addc_u32 s9, s41, 0
	s_add_i32 s54, s52, 0x4000
	global_load_lds_dwordx4 v136, s[40:41]
	s_mov_b32 m0, s54
	s_add_i32 s55, s52, 0x6000
	global_load_lds_dwordx4 v132, s[8:9]
	s_mov_b32 m0, s55
	v_mov_b32_e32 v135, 0
	global_load_lds_dwordx4 v136, s[8:9]
	v_mov_b32_e32 v139, v135
	v_mov_b32_e32 v133, v135
	v_mov_b32_e32 v137, v135
	s_cmp_eq_u32 s4, 1
	s_mov_b32 s1, 0
	v_lshl_add_u64 v[6:7], s[42:43], 0, v[134:135]
	v_lshl_add_u64 v[4:5], s[42:43], 0, v[138:139]
	v_lshl_add_u64 v[0:1], s[40:41], 0, v[132:133]
	s_cselect_b64 s[8:9], -1, 0
	v_lshl_add_u64 v[2:3], s[40:41], 0, v[136:137]
	s_mov_b64 s[10:11], 0x80
	s_and_b32 s56, s5, 3
	s_add_i32 m0, s52, 0x18000
	v_lshl_add_u64 v[6:7], v[6:7], 0, s[10:11]
	s_lshl_b32 s5, s4, 13
	s_lshl_b32 s7, s56, 12
	global_load_lds_dwordx4 v[6:7], off
	v_lshl_add_u64 v[4:5], v[4:5], 0, s[10:11]
	s_add_i32 m0, s52, 0x1a000
	s_add_i32 s57, s52, 0x8000
	s_add_i32 s58, s52, 0xa000
	global_load_lds_dwordx4 v[4:5], off
	v_lshl_add_u64 v[0:1], v[0:1], 0, s[10:11]
	s_mov_b32 m0, s57
	s_add_u32 s12, s42, 0x40080
	global_load_lds_dwordx4 v[0:1], off
	v_lshl_add_u64 v[0:1], v[2:3], 0, s[10:11]
	s_mov_b32 m0, s58
	s_addc_u32 s13, s43, 0
	global_load_lds_dwordx4 v[0:1], off
	s_add_i32 m0, s52, 0x1c000
	v_lshl_add_u64 v[0:1], s[12:13], 0, v[134:135]
	global_load_lds_dwordx4 v[0:1], off
	v_lshl_add_u64 v[0:1], s[12:13], 0, v[138:139]
	s_add_i32 m0, s52, 0x1e000
	v_lshlrev_b32_e32 v4, 2, v128
	global_load_lds_dwordx4 v[0:1], off
	s_cmp_lg_u32 s4, 1
	s_cbranch_scc1 .LBB0_959
	s_barrier
.LBB0_959:
	s_waitcnt vmcnt(8)
	s_barrier
	v_bfe_u32 v0, v128, 4, 2
	v_and_b32_e32 v1, 15, v128
	v_lshlrev_b32_e32 v3, 4, v0
	v_lshl_or_b32 v131, s4, 6, v1
	v_lshl_or_b32 v1, v1, 6, v3
	v_and_b32_e32 v4, 32, v4
	v_lshlrev_b32_e32 v5, 6, v128
	s_movk_i32 s4, 0x3c0
	v_lshlrev_b32_e32 v2, 3, v0
	v_bitop3_b32 v1, v1, s5, v4 bitop3:0xde
	v_and_or_b32 v3, v5, s4, v3
	v_cmp_eq_u32_e64 s[4:5], 0, v0
	v_lshlrev_b32_e32 v0, 8, v128
	v_lshl_or_b32 v153, s56, 5, v2
	v_and_b32_e32 v0, 0x38000, v0
	v_lshlrev_b32_e32 v2, 11, v10
	v_or3_b32 v0, v8, v0, v2
	v_add_u32_e32 v140, v0, v9
	v_lshlrev_b32_e32 v0, 4, v11
	v_and_b32_e32 v0, 0x78000, v0
	s_waitcnt vmcnt(6)
	s_cmpk_lt_u32 s6, 0x100
	v_or3_b32 v0, v8, v0, v2
	v_bitop3_b32 v152, s7, v3, v4 bitop3:0xf6
	s_cselect_b64 s[22:23], -1, 0
	v_add_u32_e32 v142, v0, v9
	s_add_i32 s64, 0, 0x10000
	s_add_i32 s65, 0, 0x14000
	v_mbcnt_lo_u32_b32 v0, -1, 0
	s_ashr_i32 s59, s72, 31
	s_mov_b32 s62, s72
	s_ashr_i32 s63, s2, 31
	v_mov_b32_e32 v141, v135
	v_mov_b32_e32 v143, v135
	v_mov_b64_e32 v[144:145], 0x200
	v_mov_b64_e32 v[146:147], 0x1ff
	v_add_u32_e32 v154, s64, v152
	v_add_u32_e32 v155, s65, v152
	v_add_u32_e32 v157, 0, v1
	v_mbcnt_hi_u32_b32 v158, -1, v0
	s_mov_b32 s66, 0
	s_barrier
	s_branch .LBB0_962

.LBB0_1050:
	s_or_b64 exec, exec, s[0:1]
	s_cmpk_gt_i32 s2, 0xaff
	v_readfirstlane_b32 s5, v128
	s_waitcnt lgkmcnt(0)
	s_barrier
	s_cbranch_scc1 .LBB0_1066
	v_lshrrev_b32_e32 v0, 5, v128
	v_lshrrev_b32_e32 v2, 1, v128
	v_and_b32_e32 v0, 4, v0
	v_bfe_u32 v1, v128, 2, 2
	v_and_b32_e32 v12, 24, v2
	v_or3_b32 v0, v0, v1, v12
	v_lshlrev_b32_e32 v1, 4, v128
	v_add_u32_e32 v9, 0x2000, v1
	v_lshrrev_b32_e32 v2, 7, v9
	s_movk_i32 s0, 0xe0
	v_and_b32_e32 v4, 32, v128
	v_and_or_b32 v3, v2, s0, v0
	v_bitop3_b32 v10, v1, v4, 48 bitop3:0x6c
	v_and_b32_e32 v11, 64, v128
	v_bfe_u32 v13, v128, 2, 4
	s_movk_i32 s0, 0xf0
	s_lshr_b32 s6, s5, 6
	v_or_b32_e32 v1, v10, v11
	v_and_or_b32 v2, v2, s0, v13
	s_lshr_b32 s10, s5, 8
	s_lshl_b32 s48, s6, 10
	v_lshl_or_b32 v134, v2, 11, v1
	v_lshrrev_b32_e32 v2, 3, v128
	s_movk_i32 s0, 0x60
	s_add_u32 s49, s70, 0x2180000
	v_and_or_b32 v0, v2, s0, v0
	s_movk_i32 s0, 0x70
	s_addc_u32 s50, s71, 0
	v_lshl_or_b32 v136, v0, 11, v1
	v_and_or_b32 v0, v2, s0, v13
	s_lshr_b32 s0, s3, 29
	s_add_i32 s0, s2, s0
	s_ashr_i32 s1, s0, 3
	s_and_b32 s0, s0, -8
	s_sub_i32 s0, s2, s0
	s_cmp_lt_i32 s0, 0
	s_movk_i32 s51, 0x161
	s_cselect_b32 s4, s51, 0x160
	s_mul_i32 s0, s0, s4
	s_add_i32 s0, s0, s1
	s_mul_hi_i32 s1, s0, 0x2e8ba2e9
	s_lshr_b32 s4, s1, 31
	s_ashr_i32 s1, s1, 5
	s_add_i32 s1, s1, s4
	s_lshl_b32 s7, s1, 3
	s_mulk_i32 s1, 0xb0
	s_sub_i32 s0, s0, s1
	s_bfe_u32 s1, s0, 0x3001c
	s_add_i32 s1, s0, s1
	s_sext_i32_i16 s4, s1
	s_and_b32 s1, s1, 0xfff8
	s_sub_i32 s0, s0, s1
	s_sext_i32_i16 s0, s0
	s_lshr_b32 s4, s4, 3
	s_add_i32 s30, s7, s0
	s_ashr_i32 s31, s30, 31
	s_bfe_i64 s[8:9], s[4:5], 0x100000
	s_lshl_b64 s[0:1], s[30:31], 19
	s_lshl_b64 s[8:9], s[8:9], 19
	s_add_u32 s38, s49, s8
	s_addc_u32 s39, s50, s9
	s_add_i32 s31, s48, 0
	s_add_i32 m0, s31, 0x10000
	v_lshl_or_b32 v132, v3, 11, v1
	global_load_lds_dwordx4 v136, s[38:39]
	s_add_i32 m0, s31, 0x12000
	s_add_u32 s8, s38, 0x40000
	global_load_lds_dwordx4 v132, s[38:39]
	s_addc_u32 s9, s39, 0
	s_add_i32 m0, s31, 0x14000
	v_lshl_or_b32 v138, v0, 11, v1
	global_load_lds_dwordx4 v136, s[8:9]
	s_add_i32 m0, s31, 0x16000
	s_add_u32 s36, s14, s0
	s_addc_u32 s37, s15, s1
	s_add_i32 s52, s31, 0x2000
	global_load_lds_dwordx4 v132, s[8:9]
	s_mov_b32 m0, s31
	s_add_u32 s0, s36, 0x40000
	global_load_lds_dwordx4 v138, s[36:37]
	s_mov_b32 m0, s52
	s_addc_u32 s1, s37, 0
	s_add_i32 s53, s31, 0x4000
	global_load_lds_dwordx4 v134, s[36:37]
	s_mov_b32 m0, s53
	s_add_i32 s54, s31, 0x6000
	global_load_lds_dwordx4 v138, s[0:1]
	s_mov_b32 m0, s54
	v_mov_b32_e32 v137, 0
	global_load_lds_dwordx4 v134, s[0:1]
	v_mov_b32_e32 v133, v137
	v_mov_b32_e32 v139, v137
	v_mov_b32_e32 v135, v137
	s_cmp_eq_u32 s10, 1
	s_mov_b32 s12, 0
	v_lshl_add_u64 v[6:7], s[38:39], 0, v[136:137]
	v_lshl_add_u64 v[4:5], s[38:39], 0, v[132:133]
	v_lshl_add_u64 v[0:1], s[36:37], 0, v[138:139]
	s_cselect_b64 s[0:1], -1, 0
	v_lshl_add_u64 v[2:3], s[36:37], 0, v[134:135]
	s_lshl_b32 s6, s6, 5
	s_and_b32 s22, s6, 0x60
	s_mov_b64 s[6:7], 0x80
	s_add_i32 m0, s31, 0x18000
	v_lshl_add_u64 v[6:7], v[6:7], 0, s[6:7]
	s_lshl_b32 s11, s10, 13
	s_lshl_b32 s23, s22, 7
	global_load_lds_dwordx4 v[6:7], off
	v_lshl_add_u64 v[4:5], v[4:5], 0, s[6:7]
	s_add_i32 m0, s31, 0x1a000
	s_add_i32 s55, s31, 0x8000
	s_add_i32 s56, s31, 0xa000
	global_load_lds_dwordx4 v[4:5], off
	v_lshl_add_u64 v[0:1], v[0:1], 0, s[6:7]
	s_mov_b32 m0, s55
	s_add_u32 s8, s38, 0x40080
	global_load_lds_dwordx4 v[0:1], off
	v_lshl_add_u64 v[0:1], v[2:3], 0, s[6:7]
	s_mov_b32 m0, s56
	s_addc_u32 s9, s39, 0
	global_load_lds_dwordx4 v[0:1], off
	s_add_i32 m0, s31, 0x1c000
	v_lshl_add_u64 v[0:1], s[8:9], 0, v[136:137]
	global_load_lds_dwordx4 v[0:1], off
	v_lshl_add_u64 v[0:1], s[8:9], 0, v[132:133]
	s_add_i32 m0, s31, 0x1e000
	s_sext_i32_i16 s13, s4
	global_load_lds_dwordx4 v[0:1], off
	s_cmp_lg_u32 s10, 1
	s_cbranch_scc1 .LBB0_1053
	s_barrier
.LBB0_1053:
	s_waitcnt vmcnt(8)
	s_barrier
	v_and_b32_e32 v0, 15, v128
	v_lshlrev_b32_e32 v1, 1, v12
	v_lshl_or_b32 v131, s10, 6, v0
	v_lshl_or_b32 v2, v0, 6, v1
	v_lshlrev_b32_e32 v0, 2, v0
	v_and_b32_e32 v3, 32, v0
	v_bitop3_b32 v2, v2, s11, v3 bitop3:0xde
	v_lshlrev_b32_e32 v3, 6, v128
	s_movk_i32 s4, 0x3c0
	s_cmpk_lt_u32 s5, 0x100
	v_and_or_b32 v1, v3, s4, v1
	s_cselect_b64 s[8:9], -1, 0
	s_lshl_b32 s4, s10, 8
	s_add_i32 s4, s4, 0
	s_add_i32 s4, s4, 0x20000
	v_and_b32_e32 v3, 32, v8
	v_add_u32_e32 v153, s4, v0
	v_lshlrev_b32_e32 v0, 8, v128
	v_bitop3_b32 v152, s23, v1, v3 bitop3:0xf6
	v_and_b32_e32 v0, 0x38000, v0
	v_lshlrev_b32_e32 v1, 11, v13
	v_or3_b32 v0, v10, v0, v1
	v_add_u32_e32 v140, v0, v11
	v_lshlrev_b32_e32 v0, 4, v9
	s_waitcnt vmcnt(6)
	v_and_b32_e32 v0, 0x78000, v0
	v_or3_b32 v0, v10, v0, v1
	s_add_i32 s57, 0, 0x10000
	s_add_i32 s58, 0, 0x14000
	v_or_b32_e32 v154, s22, v12
	v_mov_b32_e32 v141, v137
	v_add_u32_e32 v142, v0, v11
	v_mov_b32_e32 v143, v137
	v_mov_b64_e32 v[144:145], 0xb00
	v_mov_b64_e32 v[146:147], 0xaff
	v_add_u32_e32 v155, s57, v152
	v_add_u32_e32 v157, s58, v152
	v_add_u32_e32 v158, 0, v2
	s_movk_i32 s59, 0x1600
	s_mov_b32 s62, 0
	s_barrier
	s_branch .LBB0_1056

.LBB0_1129:
	s_waitcnt vmcnt(0)
	v_lshrrev_b32_e32 v3, 1, v128
	v_lshrrev_b32_e32 v4, 5, v128
	v_and_b32_e32 v3, 24, v3
	v_and_b32_e32 v4, 4, v4
	v_bfe_u32 v5, v128, 2, 2
	v_lshlrev_b32_e32 v0, 4, v128
	s_waitcnt lgkmcnt(0)
	v_and_b32_e32 v1, 32, v128
	v_bfe_u32 v2, v128, 2, 4
	v_or3_b32 v3, v4, v5, v3
	v_lshrrev_b32_e32 v4, 3, v128
	s_movk_i32 s0, 0x70
	v_bitop3_b32 v8, v0, v1, 48 bitop3:0x6c
	v_and_or_b32 v5, v4, s0, v2
	s_movk_i32 s0, 0x60
	v_add_u32_e32 v0, 0x2000, v0
	s_add_u32 s3, s70, 0x2c80000
	v_and_or_b32 v4, v4, s0, v3
	v_lshrrev_b32_e32 v0, 7, v0
	s_movk_i32 s0, 0xf0
	s_addc_u32 s40, s71, 0
	s_lshr_b32 s1, s6, 6
	v_and_b32_e32 v9, 64, v128
	v_and_or_b32 v2, v0, s0, v2
	s_movk_i32 s0, 0xe0
	v_or_b32_e32 v1, v8, v9
	v_and_or_b32 v0, v0, s0, v3
	s_lshr_b32 s0, s6, 8
	s_lshl_b32 s41, s1, 10
	s_mul_i32 s5, s8, 0x160000
	v_lshrrev_b32_e32 v1, 1, v1
	v_mul_u32_u24_e32 v4, 0xb00, v4
	s_mul_hi_i32 s4, s8, 0x160000
	s_add_u32 s36, s3, s5
	v_or_b32_e32 v4, v4, v1
	s_addc_u32 s37, s40, s4
	s_add_i32 s42, s41, 0
	v_lshlrev_b32_e32 v134, 1, v4
	v_mul_u32_u24_e32 v0, 0xb00, v0
	s_add_i32 m0, s42, 0x10000
	v_or_b32_e32 v0, v0, v1
	global_load_lds_dwordx4 v134, s[36:37]
	s_add_i32 m0, s42, 0x12000
	v_lshlrev_b32_e32 v138, 1, v0
	s_add_u32 s4, s36, 0xb0000
	global_load_lds_dwordx4 v138, s[36:37]
	s_addc_u32 s5, s37, 0
	s_add_i32 m0, s42, 0x14000
	s_mul_i32 s9, s12, 0x160000
	global_load_lds_dwordx4 v134, s[4:5]
	s_add_i32 m0, s42, 0x16000
	v_mul_u32_u24_e32 v10, 0xb00, v5
	s_mul_hi_i32 s7, s12, 0x160000
	s_add_u32 s30, s16, s9
	v_or_b32_e32 v5, v1, v10
	v_mul_u32_u24_e32 v11, 0xb00, v2
	s_addc_u32 s31, s17, s7
	s_add_i32 s43, s42, 0x2000
	v_lshlrev_b32_e32 v132, 1, v5
	v_or_b32_e32 v2, v11, v1
	global_load_lds_dwordx4 v138, s[4:5]
	s_mov_b32 m0, s42
	s_add_u32 s4, s30, 0xb0000
	v_lshlrev_b32_e32 v136, 1, v2
	global_load_lds_dwordx4 v132, s[30:31]
	s_mov_b32 m0, s43
	s_addc_u32 s5, s31, 0
	s_add_i32 s48, s42, 0x4000
	global_load_lds_dwordx4 v136, s[30:31]
	s_mov_b32 m0, s48
	s_add_i32 s49, s42, 0x6000
	global_load_lds_dwordx4 v132, s[4:5]
	s_mov_b32 m0, s49
	v_mov_b32_e32 v135, 0
	global_load_lds_dwordx4 v136, s[4:5]
	v_mov_b32_e32 v139, v135
	v_mov_b32_e32 v133, v135
	v_mov_b32_e32 v137, v135
	s_cmp_eq_u32 s0, 1
	s_mov_b32 s9, 0
	v_lshl_add_u64 v[6:7], s[36:37], 0, v[134:135]
	v_lshl_add_u64 v[4:5], s[36:37], 0, v[138:139]
	v_lshl_add_u64 v[0:1], s[30:31], 0, v[132:133]
	s_cselect_b64 s[10:11], -1, 0
	v_lshl_add_u64 v[2:3], s[30:31], 0, v[136:137]
	s_mov_b64 s[22:23], 0x80
	s_and_b32 s50, s1, 3
	s_add_i32 m0, s42, 0x18000
	v_lshl_add_u64 v[6:7], v[6:7], 0, s[22:23]
	s_lshl_b32 s1, s0, 13
	s_lshl_b32 s7, s50, 12
	global_load_lds_dwordx4 v[6:7], off
	v_lshl_add_u64 v[4:5], v[4:5], 0, s[22:23]
	s_add_i32 m0, s42, 0x1a000
	s_add_i32 s51, s42, 0x8000
	s_add_i32 s52, s42, 0xa000
	global_load_lds_dwordx4 v[4:5], off
	v_lshl_add_u64 v[0:1], v[0:1], 0, s[22:23]
	s_mov_b32 m0, s51
	s_add_u32 s4, s36, 0xb0080
	global_load_lds_dwordx4 v[0:1], off
	v_lshl_add_u64 v[0:1], v[2:3], 0, s[22:23]
	s_mov_b32 m0, s52
	s_addc_u32 s5, s37, 0
	global_load_lds_dwordx4 v[0:1], off
	s_add_i32 m0, s42, 0x1c000
	v_lshl_add_u64 v[0:1], s[4:5], 0, v[134:135]
	global_load_lds_dwordx4 v[0:1], off
	v_lshl_add_u64 v[0:1], s[4:5], 0, v[138:139]
	s_add_i32 m0, s42, 0x1e000
	v_lshlrev_b32_e32 v4, 2, v128
	global_load_lds_dwordx4 v[0:1], off
	s_cmp_lg_u32 s0, 1
	s_cbranch_scc1 .LBB0_1131
	s_barrier
.LBB0_1131:
	s_waitcnt vmcnt(8)
	s_barrier
	v_bfe_u32 v0, v128, 4, 2
	v_and_b32_e32 v1, 15, v128
	v_lshl_or_b32 v131, s0, 6, v1
	v_lshlrev_b32_e32 v2, 3, v0
	v_lshlrev_b32_e32 v3, 4, v0
	v_lshlrev_b32_e32 v5, 6, v128
	s_movk_i32 s0, 0x3c0
	v_cmp_eq_u32_e64 s[4:5], 0, v0
	v_add_u16_e32 v0, v8, v9
	v_lshl_or_b32 v1, v1, 6, v3
	v_and_b32_e32 v4, 32, v4
	v_and_or_b32 v3, v5, s0, v3
	s_waitcnt vmcnt(6)
	s_cmpk_lt_u32 s6, 0x100
	v_lshrrev_b16_e32 v0, 1, v0
	v_bitop3_b32 v1, v1, s1, v4 bitop3:0xde
	v_bitop3_b32 v152, s7, v3, v4 bitop3:0xf6
	s_cselect_b64 s[26:27], -1, 0
	v_add_lshl_u32 v140, v10, v0, 1
	v_add_lshl_u32 v142, v11, v0, 1
	s_add_i32 s56, 0, 0x10000
	s_add_i32 s57, 0, 0x14000
	v_mbcnt_lo_u32_b32 v0, -1, 0
	v_lshl_or_b32 v153, s50, 5, v2
	s_ashr_i32 s53, s72, 31
	s_mov_b32 s54, s72
	s_ashr_i32 s55, s2, 31
	v_mov_b32_e32 v141, v135
	v_mov_b32_e32 v143, v135
	v_mov_b64_e32 v[144:145], 0x200
	v_mov_b64_e32 v[146:147], 0x1ff
	v_add_u32_e32 v154, s56, v152
	v_add_u32_e32 v155, s57, v152
	v_add_u32_e32 v157, 0, v1
	v_mbcnt_hi_u32_b32 v158, -1, v0
	s_mov_b32 s58, 0
	s_barrier
	s_branch .LBB0_1134

.LBB0_1226:
	s_or_b64 exec, exec, s[0:1]
	s_cmpk_gt_i32 s2, 0x5ff
	v_readfirstlane_b32 s5, v128
	s_waitcnt lgkmcnt(0)
	s_barrier
	s_cbranch_scc1 .LBB0_1242
	v_lshrrev_b32_e32 v0, 5, v128
	v_lshrrev_b32_e32 v2, 1, v128
	v_and_b32_e32 v0, 4, v0
	v_bfe_u32 v1, v128, 2, 2
	v_and_b32_e32 v12, 24, v2
	v_or3_b32 v0, v0, v1, v12
	v_lshlrev_b32_e32 v1, 4, v128
	v_add_u32_e32 v9, 0x2000, v1
	v_lshrrev_b32_e32 v2, 7, v9
	s_movk_i32 s0, 0xe0
	v_and_b32_e32 v4, 32, v128
	v_and_or_b32 v3, v2, s0, v0
	v_bitop3_b32 v10, v1, v4, 48 bitop3:0x6c
	v_and_b32_e32 v11, 64, v128
	v_bfe_u32 v13, v128, 2, 4
	s_movk_i32 s0, 0xf0
	s_lshr_b32 s6, s5, 6
	v_or_b32_e32 v1, v10, v11
	v_and_or_b32 v2, v2, s0, v13
	s_lshr_b32 s10, s5, 8
	s_lshl_b32 s48, s6, 10
	v_lshl_or_b32 v134, v2, 11, v1
	v_lshrrev_b32_e32 v2, 3, v128
	s_movk_i32 s0, 0x60
	s_add_u32 s49, s70, 0x3200000
	v_and_or_b32 v0, v2, s0, v0
	s_movk_i32 s0, 0x70
	s_addc_u32 s50, s71, 0
	v_lshl_or_b32 v136, v0, 11, v1
	v_and_or_b32 v0, v2, s0, v13
	s_lshr_b32 s0, s3, 29
	s_add_i32 s0, s2, s0
	s_ashr_i32 s1, s0, 3
	s_and_b32 s0, s0, -8
	s_sub_i32 s0, s2, s0
	s_cmp_lt_i32 s0, 0
	s_movk_i32 s51, 0xc1
	s_cselect_b32 s4, s51, 0xc0
	s_mul_i32 s0, s0, s4
	s_add_i32 s0, s0, s1
	s_mul_hi_i32 s1, s0, 0x2aaaaaab
	s_lshr_b32 s4, s1, 31
	s_ashr_i32 s1, s1, 4
	s_add_i32 s1, s1, s4
	s_lshl_b32 s7, s1, 3
	s_mulk_i32 s1, 0x60
	s_sub_i32 s0, s0, s1
	s_bfe_i32 s1, s0, 0x80000
	s_bfe_u32 s1, s1, 0x3000c
	s_add_i32 s1, s0, s1
	s_bfe_i32 s4, s1, 0x80000
	s_and_b32 s1, s1, 0xf8
	s_sub_i32 s0, s0, s1
	s_sext_i32_i16 s4, s4
	s_sext_i32_i8 s0, s0
	s_lshr_b32 s4, s4, 3
	s_add_i32 s30, s7, s0
	s_ashr_i32 s31, s30, 31
	s_bfe_i64 s[8:9], s[4:5], 0x100000
	s_lshl_b64 s[0:1], s[30:31], 19
	s_lshl_b64 s[8:9], s[8:9], 19
	s_add_u32 s38, s49, s8
	s_addc_u32 s39, s50, s9
	s_add_i32 s31, s48, 0
	s_add_i32 m0, s31, 0x10000
	v_lshl_or_b32 v132, v3, 11, v1
	global_load_lds_dwordx4 v136, s[38:39]
	s_add_i32 m0, s31, 0x12000
	s_add_u32 s8, s38, 0x40000
	global_load_lds_dwordx4 v132, s[38:39]
	s_addc_u32 s9, s39, 0
	s_add_i32 m0, s31, 0x14000
	v_lshl_or_b32 v138, v0, 11, v1
	global_load_lds_dwordx4 v136, s[8:9]
	s_add_i32 m0, s31, 0x16000
	s_add_u32 s36, s14, s0
	s_addc_u32 s37, s15, s1
	s_add_i32 s52, s31, 0x2000
	global_load_lds_dwordx4 v132, s[8:9]
	s_mov_b32 m0, s31
	s_add_u32 s0, s36, 0x40000
	global_load_lds_dwordx4 v138, s[36:37]
	s_mov_b32 m0, s52
	s_addc_u32 s1, s37, 0
	s_add_i32 s53, s31, 0x4000
	global_load_lds_dwordx4 v134, s[36:37]
	s_mov_b32 m0, s53
	s_add_i32 s54, s31, 0x6000
	global_load_lds_dwordx4 v138, s[0:1]
	s_mov_b32 m0, s54
	v_mov_b32_e32 v137, 0
	global_load_lds_dwordx4 v134, s[0:1]
	v_mov_b32_e32 v133, v137
	v_mov_b32_e32 v139, v137
	v_mov_b32_e32 v135, v137
	s_cmp_eq_u32 s10, 1
	s_mov_b32 s62, 0
	v_lshl_add_u64 v[6:7], s[38:39], 0, v[136:137]
	v_lshl_add_u64 v[4:5], s[38:39], 0, v[132:133]
	v_lshl_add_u64 v[0:1], s[36:37], 0, v[138:139]
	s_cselect_b64 s[0:1], -1, 0
	v_lshl_add_u64 v[2:3], s[36:37], 0, v[134:135]
	s_lshl_b32 s6, s6, 5
	s_and_b32 s22, s6, 0x60
	s_mov_b64 s[6:7], 0x80
	s_add_i32 m0, s31, 0x18000
	v_lshl_add_u64 v[6:7], v[6:7], 0, s[6:7]
	s_lshl_b32 s11, s10, 13
	s_lshl_b32 s23, s22, 7
	global_load_lds_dwordx4 v[6:7], off
	v_lshl_add_u64 v[4:5], v[4:5], 0, s[6:7]
	s_add_i32 m0, s31, 0x1a000
	s_add_i32 s12, s31, 0x8000
	s_add_i32 s13, s31, 0xa000
	global_load_lds_dwordx4 v[4:5], off
	v_lshl_add_u64 v[0:1], v[0:1], 0, s[6:7]
	s_mov_b32 m0, s12
	s_add_u32 s8, s38, 0x40080
	global_load_lds_dwordx4 v[0:1], off
	v_lshl_add_u64 v[0:1], v[2:3], 0, s[6:7]
	s_mov_b32 m0, s13
	s_addc_u32 s9, s39, 0
	global_load_lds_dwordx4 v[0:1], off
	s_add_i32 m0, s31, 0x1c000
	v_lshl_add_u64 v[0:1], s[8:9], 0, v[136:137]
	global_load_lds_dwordx4 v[0:1], off
	v_lshl_add_u64 v[0:1], s[8:9], 0, v[132:133]
	s_add_i32 m0, s31, 0x1e000
	s_sext_i32_i8 s63, s4
	global_load_lds_dwordx4 v[0:1], off
	s_cmp_lg_u32 s10, 1
	s_cbranch_scc1 .LBB0_1229
	s_barrier
.LBB0_1229:
	s_waitcnt vmcnt(8)
	s_barrier
	v_and_b32_e32 v0, 15, v128
	v_lshlrev_b32_e32 v1, 1, v12
	v_lshl_or_b32 v131, s10, 6, v0
	v_lshl_or_b32 v2, v0, 6, v1
	v_lshlrev_b32_e32 v0, 2, v0
	v_and_b32_e32 v3, 32, v0
	v_bitop3_b32 v2, v2, s11, v3 bitop3:0xde
	v_lshlrev_b32_e32 v3, 6, v128
	s_movk_i32 s4, 0x3c0
	s_cmpk_lt_u32 s5, 0x100
	v_and_or_b32 v1, v3, s4, v1
	s_cselect_b64 s[8:9], -1, 0
	s_lshl_b32 s4, s10, 8
	s_add_i32 s4, s4, 0
	s_add_i32 s4, s4, 0x20000
	v_and_b32_e32 v3, 32, v8
	v_add_u32_e32 v153, s4, v0
	v_lshlrev_b32_e32 v0, 8, v128
	v_bitop3_b32 v152, s23, v1, v3 bitop3:0xf6
	v_and_b32_e32 v0, 0x38000, v0
	v_lshlrev_b32_e32 v1, 11, v13
	v_or3_b32 v0, v10, v0, v1
	v_add_u32_e32 v140, v0, v11
	v_lshlrev_b32_e32 v0, 4, v9
	s_waitcnt vmcnt(6)
	v_and_b32_e32 v0, 0x78000, v0
	v_or3_b32 v0, v10, v0, v1
	s_add_i32 s55, 0, 0x10000
	s_add_i32 s56, 0, 0x14000
	v_or_b32_e32 v154, s22, v12
	v_mov_b32_e32 v141, v137
	v_add_u32_e32 v142, v0, v11
	v_mov_b32_e32 v143, v137
	v_mov_b64_e32 v[144:145], 0x600
	v_mov_b64_e32 v[146:147], 0x5ff
	v_add_u32_e32 v155, s55, v152
	v_add_u32_e32 v157, s56, v152
	v_add_u32_e32 v158, 0, v2
	s_movk_i32 s57, 0x1800
	s_mov_b32 s58, 0
	s_barrier
	s_branch .LBB0_1232

.LBB0_1545:
	s_waitcnt vmcnt(0)
	v_lshrrev_b32_e32 v2, 1, v128
	v_lshrrev_b32_e32 v3, 5, v128
	v_and_b32_e32 v2, 24, v2
	v_and_b32_e32 v3, 4, v3
	v_bfe_u32 v4, v128, 2, 2
	v_lshlrev_b32_e32 v0, 4, v128
	s_waitcnt lgkmcnt(0)
	v_and_b32_e32 v1, 32, v128
	v_bfe_u32 v10, v128, 2, 4
	v_or3_b32 v2, v3, v4, v2
	v_lshrrev_b32_e32 v3, 3, v128
	s_movk_i32 s1, 0x70
	v_bitop3_b32 v8, v0, v1, 48 bitop3:0x6c
	v_and_b32_e32 v9, 64, v128
	v_and_or_b32 v4, v3, s1, v10
	s_movk_i32 s1, 0x60
	v_add_u32_e32 v11, 0x2000, v0
	v_or_b32_e32 v1, v8, v9
	v_and_or_b32 v3, v3, s1, v2
	v_lshrrev_b32_e32 v0, 7, v11
	s_movk_i32 s1, 0xf0
	s_add_u32 s3, s70, 0x3800000
	v_lshl_or_b32 v132, v3, 11, v1
	v_and_or_b32 v3, v0, s1, v10
	s_movk_i32 s1, 0xe0
	s_addc_u32 s46, s71, 0
	s_lshr_b32 s5, s6, 6
	v_and_or_b32 v0, v0, s1, v2
	s_ashr_i32 s39, s38, 31
	s_ashr_i32 s1, s0, 31
	s_lshr_b32 s4, s6, 8
	s_lshl_b32 s47, s5, 10
	s_lshl_b64 s[8:9], s[38:39], 19
	s_lshl_b64 s[10:11], s[0:1], 19
	s_add_u32 s42, s3, s10
	s_addc_u32 s43, s46, s11
	s_add_i32 s48, s47, 0
	s_add_i32 m0, s48, 0x10000
	v_lshl_or_b32 v136, v0, 11, v1
	global_load_lds_dwordx4 v132, s[42:43]
	s_add_i32 m0, s48, 0x12000
	s_add_u32 s10, s42, 0x40000
	global_load_lds_dwordx4 v136, s[42:43]
	s_addc_u32 s11, s43, 0
	s_add_i32 m0, s48, 0x14000
	v_lshl_or_b32 v130, v4, 11, v1
	global_load_lds_dwordx4 v132, s[10:11]
	s_add_i32 m0, s48, 0x16000
	s_add_u32 s40, s20, s8
	s_addc_u32 s41, s21, s9
	s_add_i32 s49, s48, 0x2000
	global_load_lds_dwordx4 v136, s[10:11]
	s_mov_b32 m0, s48
	s_add_u32 s8, s40, 0x40000
	v_lshl_or_b32 v134, v3, 11, v1
	global_load_lds_dwordx4 v130, s[40:41]
	s_mov_b32 m0, s49
	s_addc_u32 s9, s41, 0
	s_add_i32 s50, s48, 0x4000
	global_load_lds_dwordx4 v134, s[40:41]
	s_mov_b32 m0, s50
	s_add_i32 s51, s48, 0x6000
	global_load_lds_dwordx4 v130, s[8:9]
	s_mov_b32 m0, s51
	v_mov_b32_e32 v133, 0
	global_load_lds_dwordx4 v134, s[8:9]
	v_mov_b32_e32 v137, v133
	v_mov_b32_e32 v131, v133
	v_mov_b32_e32 v135, v133
	s_cmp_eq_u32 s4, 1
	s_mov_b32 s1, 0
	v_lshl_add_u64 v[6:7], s[42:43], 0, v[132:133]
	v_lshl_add_u64 v[4:5], s[42:43], 0, v[136:137]
	v_lshl_add_u64 v[0:1], s[40:41], 0, v[130:131]
	s_cselect_b64 s[8:9], -1, 0
	v_lshl_add_u64 v[2:3], s[40:41], 0, v[134:135]
	s_mov_b64 s[10:11], 0x80
	s_and_b32 s52, s5, 3
	s_add_i32 m0, s48, 0x18000
	v_lshl_add_u64 v[6:7], v[6:7], 0, s[10:11]
	s_lshl_b32 s5, s4, 13
	s_lshl_b32 s7, s52, 12
	global_load_lds_dwordx4 v[6:7], off
	v_lshl_add_u64 v[4:5], v[4:5], 0, s[10:11]
	s_add_i32 m0, s48, 0x1a000
	s_add_i32 s53, s48, 0x8000
	s_add_i32 s54, s48, 0xa000
	global_load_lds_dwordx4 v[4:5], off
	v_lshl_add_u64 v[0:1], v[0:1], 0, s[10:11]
	s_mov_b32 m0, s53
	s_add_u32 s12, s42, 0x40080
	global_load_lds_dwordx4 v[0:1], off
	v_lshl_add_u64 v[0:1], v[2:3], 0, s[10:11]
	s_mov_b32 m0, s54
	s_addc_u32 s13, s43, 0
	global_load_lds_dwordx4 v[0:1], off
	s_add_i32 m0, s48, 0x1c000
	v_lshl_add_u64 v[0:1], s[12:13], 0, v[132:133]
	global_load_lds_dwordx4 v[0:1], off
	v_lshl_add_u64 v[0:1], s[12:13], 0, v[136:137]
	s_add_i32 m0, s48, 0x1e000
	v_lshlrev_b32_e32 v4, 2, v128
	global_load_lds_dwordx4 v[0:1], off
	s_cmp_lg_u32 s4, 1
	s_cbranch_scc1 .LBB0_1547
	s_barrier
.LBB0_1547:
	s_waitcnt vmcnt(8)
	s_barrier
	v_bfe_u32 v0, v128, 4, 2
	v_and_b32_e32 v1, 15, v128
	v_lshlrev_b32_e32 v3, 4, v0
	v_lshl_or_b32 v150, s4, 6, v1
	v_lshl_or_b32 v1, v1, 6, v3
	v_and_b32_e32 v4, 32, v4
	v_lshlrev_b32_e32 v5, 6, v128
	s_movk_i32 s4, 0x3c0
	v_lshlrev_b32_e32 v2, 3, v0
	v_bitop3_b32 v1, v1, s5, v4 bitop3:0xde
	v_and_or_b32 v3, v5, s4, v3
	v_cmp_eq_u32_e64 s[4:5], 0, v0
	v_lshlrev_b32_e32 v0, 8, v128
	v_lshl_or_b32 v152, s52, 5, v2
	v_and_b32_e32 v0, 0x38000, v0
	v_lshlrev_b32_e32 v2, 11, v10
	v_or3_b32 v0, v8, v0, v2
	v_add_u32_e32 v138, v0, v9
	v_lshlrev_b32_e32 v0, 4, v11
	v_and_b32_e32 v0, 0x78000, v0
	s_waitcnt vmcnt(6)
	s_cmpk_lt_u32 s6, 0x100
	v_or3_b32 v0, v8, v0, v2
	v_bitop3_b32 v151, s7, v3, v4 bitop3:0xf6
	s_cselect_b64 s[22:23], -1, 0
	v_add_u32_e32 v140, v0, v9
	s_add_i32 s58, 0, 0x10000
	s_add_i32 s59, 0, 0x14000
	v_mbcnt_lo_u32_b32 v0, -1, 0
	s_ashr_i32 s55, s72, 31
	s_mov_b32 s56, s72
	s_ashr_i32 s57, s2, 31
	v_mov_b32_e32 v139, v133
	v_mov_b32_e32 v141, v133
	v_mov_b64_e32 v[142:143], 0x200
	v_mov_b64_e32 v[144:145], 0x1ff
	v_add_u32_e32 v153, s58, v151
	v_add_u32_e32 v154, s59, v151
	v_add_u32_e32 v155, 0, v1
	v_mbcnt_hi_u32_b32 v157, -1, v0
	s_mov_b32 s60, 0
	s_barrier
	s_branch .LBB0_1550

.LBB0_1638:
	s_or_b64 exec, exec, s[0:1]
	s_cmpk_gt_i32 s2, 0xaff
	v_readfirstlane_b32 s5, v128
	s_waitcnt lgkmcnt(0)
	s_barrier
	s_cbranch_scc1 .LBB0_1654
	v_lshrrev_b32_e32 v0, 5, v128
	v_lshrrev_b32_e32 v2, 1, v128
	v_and_b32_e32 v0, 4, v0
	v_bfe_u32 v1, v128, 2, 2
	v_and_b32_e32 v12, 24, v2
	v_or3_b32 v0, v0, v1, v12
	v_lshlrev_b32_e32 v1, 4, v128
	v_add_u32_e32 v9, 0x2000, v1
	v_lshrrev_b32_e32 v2, 7, v9
	s_movk_i32 s0, 0xe0
	v_and_b32_e32 v4, 32, v128
	v_and_or_b32 v3, v2, s0, v0
	v_bitop3_b32 v10, v1, v4, 48 bitop3:0x6c
	v_and_b32_e32 v11, 64, v128
	v_bfe_u32 v13, v128, 2, 4
	s_movk_i32 s0, 0xf0
	s_lshr_b32 s6, s5, 6
	v_or_b32_e32 v1, v10, v11
	v_and_or_b32 v2, v2, s0, v13
	s_lshr_b32 s10, s5, 8
	s_lshl_b32 s44, s6, 10
	v_lshl_or_b32 v132, v2, 11, v1
	v_lshrrev_b32_e32 v2, 3, v128
	s_movk_i32 s0, 0x60
	s_add_u32 s45, s70, 0x3a00000
	v_and_or_b32 v0, v2, s0, v0
	s_movk_i32 s0, 0x70
	s_addc_u32 s46, s71, 0
	v_lshl_or_b32 v134, v0, 11, v1
	v_and_or_b32 v0, v2, s0, v13
	s_lshr_b32 s0, s3, 29
	s_add_i32 s0, s2, s0
	s_ashr_i32 s1, s0, 3
	s_and_b32 s0, s0, -8
	s_sub_i32 s0, s2, s0
	s_cmp_lt_i32 s0, 0
	s_movk_i32 s47, 0x161
	s_cselect_b32 s4, s47, 0x160
	s_mul_i32 s0, s0, s4
	s_add_i32 s0, s0, s1
	s_mul_hi_i32 s1, s0, 0x2e8ba2e9
	s_lshr_b32 s4, s1, 31
	s_ashr_i32 s1, s1, 5
	s_add_i32 s1, s1, s4
	s_lshl_b32 s7, s1, 3
	s_mulk_i32 s1, 0xb0
	s_sub_i32 s0, s0, s1
	s_bfe_u32 s1, s0, 0x3001c
	s_add_i32 s1, s0, s1
	s_sext_i32_i16 s4, s1
	s_and_b32 s1, s1, 0xfff8
	s_sub_i32 s0, s0, s1
	s_sext_i32_i16 s0, s0
	s_lshr_b32 s4, s4, 3
	s_add_i32 s30, s7, s0
	s_ashr_i32 s31, s30, 31
	s_bfe_i64 s[8:9], s[4:5], 0x100000
	s_lshl_b64 s[0:1], s[30:31], 19
	s_lshl_b64 s[8:9], s[8:9], 19
	s_add_u32 s38, s45, s8
	s_addc_u32 s39, s46, s9
	s_add_i32 s31, s44, 0
	s_add_i32 m0, s31, 0x10000
	v_lshl_or_b32 v130, v3, 11, v1
	global_load_lds_dwordx4 v134, s[38:39]
	s_add_i32 m0, s31, 0x12000
	s_add_u32 s8, s38, 0x40000
	global_load_lds_dwordx4 v130, s[38:39]
	s_addc_u32 s9, s39, 0
	s_add_i32 m0, s31, 0x14000
	v_lshl_or_b32 v136, v0, 11, v1
	global_load_lds_dwordx4 v134, s[8:9]
	s_add_i32 m0, s31, 0x16000
	s_add_u32 s36, s14, s0
	s_addc_u32 s37, s15, s1
	s_add_i32 s48, s31, 0x2000
	global_load_lds_dwordx4 v130, s[8:9]
	s_mov_b32 m0, s31
	s_add_u32 s0, s36, 0x40000
	global_load_lds_dwordx4 v136, s[36:37]
	s_mov_b32 m0, s48
	s_addc_u32 s1, s37, 0
	s_add_i32 s49, s31, 0x4000
	global_load_lds_dwordx4 v132, s[36:37]
	s_mov_b32 m0, s49
	s_add_i32 s50, s31, 0x6000
	global_load_lds_dwordx4 v136, s[0:1]
	s_mov_b32 m0, s50
	v_mov_b32_e32 v135, 0
	global_load_lds_dwordx4 v132, s[0:1]
	v_mov_b32_e32 v131, v135
	v_mov_b32_e32 v137, v135
	v_mov_b32_e32 v133, v135
	s_cmp_eq_u32 s10, 1
	s_mov_b32 s12, 0
	v_lshl_add_u64 v[6:7], s[38:39], 0, v[134:135]
	v_lshl_add_u64 v[4:5], s[38:39], 0, v[130:131]
	v_lshl_add_u64 v[0:1], s[36:37], 0, v[136:137]
	s_cselect_b64 s[0:1], -1, 0
	v_lshl_add_u64 v[2:3], s[36:37], 0, v[132:133]
	s_lshl_b32 s6, s6, 5
	s_and_b32 s22, s6, 0x60
	s_mov_b64 s[6:7], 0x80
	s_add_i32 m0, s31, 0x18000
	v_lshl_add_u64 v[6:7], v[6:7], 0, s[6:7]
	s_lshl_b32 s11, s10, 13
	s_lshl_b32 s23, s22, 7
	global_load_lds_dwordx4 v[6:7], off
	v_lshl_add_u64 v[4:5], v[4:5], 0, s[6:7]
	s_add_i32 m0, s31, 0x1a000
	s_add_i32 s51, s31, 0x8000
	s_add_i32 s52, s31, 0xa000
	global_load_lds_dwordx4 v[4:5], off
	v_lshl_add_u64 v[0:1], v[0:1], 0, s[6:7]
	s_mov_b32 m0, s51
	s_add_u32 s8, s38, 0x40080
	global_load_lds_dwordx4 v[0:1], off
	v_lshl_add_u64 v[0:1], v[2:3], 0, s[6:7]
	s_mov_b32 m0, s52
	s_addc_u32 s9, s39, 0
	global_load_lds_dwordx4 v[0:1], off
	s_add_i32 m0, s31, 0x1c000
	v_lshl_add_u64 v[0:1], s[8:9], 0, v[134:135]
	global_load_lds_dwordx4 v[0:1], off
	v_lshl_add_u64 v[0:1], s[8:9], 0, v[130:131]
	s_add_i32 m0, s31, 0x1e000
	s_sext_i32_i16 s13, s4
	global_load_lds_dwordx4 v[0:1], off
	s_cmp_lg_u32 s10, 1
	s_cbranch_scc1 .LBB0_1641
	s_barrier
.LBB0_1641:
	s_waitcnt vmcnt(8)
	s_barrier
	v_and_b32_e32 v0, 15, v128
	v_lshlrev_b32_e32 v1, 1, v12
	v_lshl_or_b32 v150, s10, 6, v0
	v_lshl_or_b32 v2, v0, 6, v1
	v_lshlrev_b32_e32 v0, 2, v0
	v_and_b32_e32 v3, 32, v0
	v_bitop3_b32 v2, v2, s11, v3 bitop3:0xde
	v_lshlrev_b32_e32 v3, 6, v128
	s_movk_i32 s4, 0x3c0
	s_cmpk_lt_u32 s5, 0x100
	v_and_or_b32 v1, v3, s4, v1
	s_cselect_b64 s[8:9], -1, 0
	s_lshl_b32 s4, s10, 8
	s_add_i32 s4, s4, 0
	s_add_i32 s4, s4, 0x20000
	v_and_b32_e32 v3, 32, v8
	v_add_u32_e32 v152, s4, v0
	v_lshlrev_b32_e32 v0, 8, v128
	v_bitop3_b32 v151, s23, v1, v3 bitop3:0xf6
	v_and_b32_e32 v0, 0x38000, v0
	v_lshlrev_b32_e32 v1, 11, v13
	v_or3_b32 v0, v10, v0, v1
	v_add_u32_e32 v138, v0, v11
	v_lshlrev_b32_e32 v0, 4, v9
	s_waitcnt vmcnt(6)
	v_and_b32_e32 v0, 0x78000, v0
	v_or3_b32 v0, v10, v0, v1
	s_add_i32 s53, 0, 0x10000
	s_add_i32 s54, 0, 0x14000
	v_or_b32_e32 v153, s22, v12
	v_mov_b32_e32 v139, v135
	v_add_u32_e32 v140, v0, v11
	v_mov_b32_e32 v141, v135
	v_mov_b64_e32 v[142:143], 0xb00
	v_mov_b64_e32 v[144:145], 0xaff
	v_add_u32_e32 v154, s53, v151
	v_add_u32_e32 v155, s54, v151
	v_add_u32_e32 v157, 0, v2
	s_movk_i32 s55, 0x1600
	s_mov_b32 s56, 0
	s_barrier
	s_branch .LBB0_1644

.LBB0_1717:
	s_waitcnt vmcnt(0)
	v_lshrrev_b32_e32 v3, 1, v128
	v_lshrrev_b32_e32 v4, 5, v128
	v_and_b32_e32 v3, 24, v3
	v_and_b32_e32 v4, 4, v4
	v_bfe_u32 v5, v128, 2, 2
	v_lshlrev_b32_e32 v0, 4, v128
	s_waitcnt lgkmcnt(0)
	v_and_b32_e32 v1, 32, v128
	v_bfe_u32 v2, v128, 2, 4
	v_or3_b32 v3, v4, v5, v3
	v_lshrrev_b32_e32 v4, 3, v128
	s_movk_i32 s0, 0x70
	v_bitop3_b32 v8, v0, v1, 48 bitop3:0x6c
	v_and_or_b32 v5, v4, s0, v2
	s_movk_i32 s0, 0x60
	v_add_u32_e32 v0, 0x2000, v0
	s_add_u32 s3, s70, 0x4500000
	v_and_or_b32 v4, v4, s0, v3
	v_lshrrev_b32_e32 v0, 7, v0
	s_movk_i32 s0, 0xf0
	s_addc_u32 s40, s71, 0
	s_lshr_b32 s1, s6, 6
	v_and_b32_e32 v9, 64, v128
	v_and_or_b32 v2, v0, s0, v2
	s_movk_i32 s0, 0xe0
	v_or_b32_e32 v1, v8, v9
	v_and_or_b32 v0, v0, s0, v3
	s_lshr_b32 s0, s6, 8
	s_lshl_b32 s41, s1, 10
	s_mul_i32 s5, s8, 0x160000
	v_lshrrev_b32_e32 v1, 1, v1
	v_mul_u32_u24_e32 v4, 0xb00, v4
	s_mul_hi_i32 s4, s8, 0x160000
	s_add_u32 s36, s3, s5
	v_or_b32_e32 v4, v4, v1
	s_addc_u32 s37, s40, s4
	s_add_i32 s42, s41, 0
	v_lshlrev_b32_e32 v132, 1, v4
	v_mul_u32_u24_e32 v0, 0xb00, v0
	s_add_i32 m0, s42, 0x10000
	v_or_b32_e32 v0, v0, v1
	global_load_lds_dwordx4 v132, s[36:37]
	s_add_i32 m0, s42, 0x12000
	v_lshlrev_b32_e32 v136, 1, v0
	s_add_u32 s4, s36, 0xb0000
	global_load_lds_dwordx4 v136, s[36:37]
	s_addc_u32 s5, s37, 0
	s_add_i32 m0, s42, 0x14000
	s_mul_i32 s9, s12, 0x160000
	global_load_lds_dwordx4 v132, s[4:5]
	s_add_i32 m0, s42, 0x16000
	v_mul_u32_u24_e32 v10, 0xb00, v5
	s_mul_hi_i32 s7, s12, 0x160000
	s_add_u32 s30, s16, s9
	v_or_b32_e32 v5, v1, v10
	v_mul_u32_u24_e32 v11, 0xb00, v2
	s_addc_u32 s31, s17, s7
	s_add_i32 s43, s42, 0x2000
	v_lshlrev_b32_e32 v130, 1, v5
	v_or_b32_e32 v2, v11, v1
	global_load_lds_dwordx4 v136, s[4:5]
	s_mov_b32 m0, s42
	s_add_u32 s4, s30, 0xb0000
	v_lshlrev_b32_e32 v134, 1, v2
	global_load_lds_dwordx4 v130, s[30:31]
	s_mov_b32 m0, s43
	s_addc_u32 s5, s31, 0
	s_add_i32 s44, s42, 0x4000
	global_load_lds_dwordx4 v134, s[30:31]
	s_mov_b32 m0, s44
	s_add_i32 s45, s42, 0x6000
	global_load_lds_dwordx4 v130, s[4:5]
	s_mov_b32 m0, s45
	v_mov_b32_e32 v133, 0
	global_load_lds_dwordx4 v134, s[4:5]
	v_mov_b32_e32 v137, v133
	v_mov_b32_e32 v131, v133
	v_mov_b32_e32 v135, v133
	s_cmp_eq_u32 s0, 1
	s_mov_b32 s9, 0
	v_lshl_add_u64 v[6:7], s[36:37], 0, v[132:133]
	v_lshl_add_u64 v[4:5], s[36:37], 0, v[136:137]
	v_lshl_add_u64 v[0:1], s[30:31], 0, v[130:131]
	s_cselect_b64 s[10:11], -1, 0
	v_lshl_add_u64 v[2:3], s[30:31], 0, v[134:135]
	s_mov_b64 s[22:23], 0x80
	s_and_b32 s46, s1, 3
	s_add_i32 m0, s42, 0x18000
	v_lshl_add_u64 v[6:7], v[6:7], 0, s[22:23]
	s_lshl_b32 s1, s0, 13
	s_lshl_b32 s7, s46, 12
	global_load_lds_dwordx4 v[6:7], off
	v_lshl_add_u64 v[4:5], v[4:5], 0, s[22:23]
	s_add_i32 m0, s42, 0x1a000
	s_add_i32 s47, s42, 0x8000
	s_add_i32 s48, s42, 0xa000
	global_load_lds_dwordx4 v[4:5], off
	v_lshl_add_u64 v[0:1], v[0:1], 0, s[22:23]
	s_mov_b32 m0, s47
	s_add_u32 s4, s36, 0xb0080
	global_load_lds_dwordx4 v[0:1], off
	v_lshl_add_u64 v[0:1], v[2:3], 0, s[22:23]
	s_mov_b32 m0, s48
	s_addc_u32 s5, s37, 0
	global_load_lds_dwordx4 v[0:1], off
	s_add_i32 m0, s42, 0x1c000
	v_lshl_add_u64 v[0:1], s[4:5], 0, v[132:133]
	global_load_lds_dwordx4 v[0:1], off
	v_lshl_add_u64 v[0:1], s[4:5], 0, v[136:137]
	s_add_i32 m0, s42, 0x1e000
	v_lshlrev_b32_e32 v4, 2, v128
	global_load_lds_dwordx4 v[0:1], off
	s_cmp_lg_u32 s0, 1
	s_cbranch_scc1 .LBB0_1719
	s_barrier
.LBB0_1719:
	s_waitcnt vmcnt(8)
	s_barrier
	v_bfe_u32 v0, v128, 4, 2
	v_and_b32_e32 v1, 15, v128
	v_lshl_or_b32 v150, s0, 6, v1
	v_lshlrev_b32_e32 v2, 3, v0
	v_lshlrev_b32_e32 v3, 4, v0
	v_lshlrev_b32_e32 v5, 6, v128
	s_movk_i32 s0, 0x3c0
	v_cmp_eq_u32_e64 s[4:5], 0, v0
	v_add_u16_e32 v0, v8, v9
	v_lshl_or_b32 v1, v1, 6, v3
	v_and_b32_e32 v4, 32, v4
	v_and_or_b32 v3, v5, s0, v3
	s_waitcnt vmcnt(6)
	s_cmpk_lt_u32 s6, 0x100
	v_lshrrev_b16_e32 v0, 1, v0
	v_bitop3_b32 v1, v1, s1, v4 bitop3:0xde
	v_bitop3_b32 v151, s7, v3, v4 bitop3:0xf6
	s_cselect_b64 s[26:27], -1, 0
	v_add_lshl_u32 v138, v10, v0, 1
	v_add_lshl_u32 v140, v11, v0, 1
	s_add_i32 s52, 0, 0x10000
	s_add_i32 s53, 0, 0x14000
	v_mbcnt_lo_u32_b32 v0, -1, 0
	v_lshl_or_b32 v152, s46, 5, v2
	s_ashr_i32 s49, s72, 31
	s_mov_b32 s50, s72
	s_ashr_i32 s51, s2, 31
	v_mov_b32_e32 v139, v133
	v_mov_b32_e32 v141, v133
	v_mov_b64_e32 v[142:143], 0x200
	v_mov_b64_e32 v[144:145], 0x1ff
	v_add_u32_e32 v153, s52, v151
	v_add_u32_e32 v154, s53, v151
	v_add_u32_e32 v155, 0, v1
	v_mbcnt_hi_u32_b32 v157, -1, v0
	s_mov_b32 s54, 0
	s_barrier
	s_branch .LBB0_1722

.LBB0_1818:
	v_lshrrev_b32_e32 v2, 1, v128
	v_and_b32_e32 v130, 24, v2
	v_lshrrev_b32_e32 v2, 5, v128
	v_and_b32_e32 v2, 4, v2
	v_bfe_u32 v3, v128, 2, 2
	v_lshlrev_b32_e32 v0, 4, v128
	v_and_b32_e32 v1, 32, v128
	v_bfe_u32 v11, v128, 2, 4
	v_or3_b32 v2, v2, v3, v130
	v_lshrrev_b32_e32 v3, 3, v128
	s_movk_i32 s1, 0x70
	v_bitop3_b32 v9, v0, v1, 48 bitop3:0x6c
	v_and_b32_e32 v10, 64, v128
	v_and_or_b32 v4, v3, s1, v11
	s_movk_i32 s1, 0x60
	v_add_u32_e32 v12, 0x2000, v0
	s_lshr_b32 s5, s8, 6
	s_lshr_b32 s4, s8, 8
	v_or_b32_e32 v1, v9, v10
	v_and_or_b32 v3, v3, s1, v2
	v_lshrrev_b32_e32 v0, 7, v12
	s_movk_i32 s1, 0xf0
	s_lshl_b32 s50, s5, 10
	v_lshl_or_b32 v134, v3, 11, v1
	v_and_or_b32 v3, v0, s1, v11
	s_movk_i32 s1, 0xe0
	s_add_u32 s51, s70, 0x4a80000
	v_and_or_b32 v0, v0, s1, v2
	s_addc_u32 s52, s71, 0
	s_ashr_i32 s7, s6, 31
	s_ashr_i32 s1, s0, 31
	s_lshl_b64 s[10:11], s[6:7], 19
	s_lshl_b64 s[12:13], s[0:1], 19
	s_add_u32 s44, s51, s12
	s_addc_u32 s45, s52, s13
	s_add_i32 s53, s50, 0
	s_add_i32 m0, s53, 0x10000
	v_lshl_or_b32 v138, v0, 11, v1
	global_load_lds_dwordx4 v134, s[44:45]
	s_add_i32 m0, s53, 0x12000
	s_add_u32 s12, s44, 0x40000
	global_load_lds_dwordx4 v138, s[44:45]
	s_addc_u32 s13, s45, 0
	s_add_i32 m0, s53, 0x14000
	v_lshl_or_b32 v132, v4, 11, v1
	global_load_lds_dwordx4 v134, s[12:13]
	s_add_i32 m0, s53, 0x16000
	s_add_u32 s42, s14, s10
	s_addc_u32 s43, s15, s11
	s_add_i32 s54, s53, 0x2000
	global_load_lds_dwordx4 v138, s[12:13]
	s_mov_b32 m0, s53
	s_add_u32 s10, s42, 0x40000
	v_lshl_or_b32 v136, v3, 11, v1
	global_load_lds_dwordx4 v132, s[42:43]
	s_mov_b32 m0, s54
	s_addc_u32 s11, s43, 0
	s_add_i32 s55, s53, 0x4000
	global_load_lds_dwordx4 v136, s[42:43]
	s_mov_b32 m0, s55
	s_add_i32 s56, s53, 0x6000
	global_load_lds_dwordx4 v132, s[10:11]
	s_mov_b32 m0, s56
	v_mov_b32_e32 v141, 0
	global_load_lds_dwordx4 v136, s[10:11]
	v_mov_b32_e32 v135, v141
	v_mov_b32_e32 v139, v141
	v_mov_b32_e32 v133, v141
	v_mov_b32_e32 v137, v141
	s_cmp_eq_u32 s4, 1
	s_mov_b32 s9, 0
	v_lshl_add_u64 v[6:7], s[44:45], 0, v[134:135]
	v_lshl_add_u64 v[4:5], s[44:45], 0, v[138:139]
	v_lshl_add_u64 v[0:1], s[42:43], 0, v[132:133]
	s_cselect_b64 s[10:11], -1, 0
	v_lshl_add_u64 v[2:3], s[42:43], 0, v[136:137]
	s_add_u32 s22, s70, 0x13700000
	s_addc_u32 s23, s71, 0
	s_lshl_b32 s5, s5, 5
	s_mov_b64 s[26:27], 0x80
	s_and_b32 s57, s5, 0x60
	s_add_i32 m0, s53, 0x18000
	v_lshl_add_u64 v[6:7], v[6:7], 0, s[26:27]
	s_lshl_b32 s1, s4, 13
	s_lshl_b32 s5, s57, 7
	global_load_lds_dwordx4 v[6:7], off
	v_lshl_add_u64 v[4:5], v[4:5], 0, s[26:27]
	s_add_i32 m0, s53, 0x1a000
	s_add_i32 s58, s53, 0x8000
	s_add_i32 s59, s53, 0xa000
	global_load_lds_dwordx4 v[4:5], off
	v_lshl_add_u64 v[0:1], v[0:1], 0, s[26:27]
	s_mov_b32 m0, s58
	s_add_u32 s12, s44, 0x40080
	global_load_lds_dwordx4 v[0:1], off
	v_lshl_add_u64 v[0:1], v[2:3], 0, s[26:27]
	s_mov_b32 m0, s59
	s_addc_u32 s13, s45, 0
	global_load_lds_dwordx4 v[0:1], off
	s_add_i32 m0, s53, 0x1c000
	v_lshl_add_u64 v[0:1], s[12:13], 0, v[134:135]
	global_load_lds_dwordx4 v[0:1], off
	v_lshl_add_u64 v[0:1], s[12:13], 0, v[138:139]
	s_add_i32 m0, s53, 0x1e000
	global_load_lds_dwordx4 v[0:1], off
	s_cmp_lg_u32 s4, 1
	s_cbranch_scc1 .LBB0_1820
	s_barrier
.LBB0_1820:
	s_waitcnt vmcnt(8)
	s_barrier
	s_cmpk_lt_u32 s8, 0x100
	v_and_b32_e32 v0, 15, v128
	v_lshlrev_b32_e32 v1, 1, v130
	v_lshl_or_b32 v131, s4, 6, v0
	v_lshl_or_b32 v2, v0, 6, v1
	v_lshlrev_b32_e32 v0, 2, v0
	v_and_b32_e32 v3, 32, v0
	v_bitop3_b32 v2, v2, s1, v3 bitop3:0xde
	v_lshlrev_b32_e32 v3, 6, v128
	s_movk_i32 s1, 0x3c0
	v_and_or_b32 v1, v3, s1, v1
	s_cselect_b64 s[28:29], -1, 0
	s_lshl_b32 s1, s4, 8
	s_add_i32 s1, s1, 0
	s_add_i32 s1, s1, 0x20000
	v_and_b32_e32 v3, 32, v8
	v_add_u32_e32 v155, s1, v0
	v_lshlrev_b32_e32 v0, 8, v128
	v_bitop3_b32 v154, s5, v1, v3 bitop3:0xf6
	v_and_b32_e32 v0, 0x38000, v0
	v_lshlrev_b32_e32 v1, 11, v11
	v_or3_b32 v0, v9, v0, v1
	v_add_u32_e32 v142, v0, v10
	v_lshlrev_b32_e32 v0, 4, v12
	s_waitcnt vmcnt(6)
	v_and_b32_e32 v0, 0x78000, v0
	v_or3_b32 v0, v9, v0, v1
	s_add_i32 s61, 0, 0x10000
	s_add_i32 s62, 0, 0x14000
	v_mov_b32_e32 v143, v141
	v_add_u32_e32 v144, v0, v10
	v_mov_b32_e32 v145, v141
	v_mov_b64_e32 v[146:147], 0x600
	v_mov_b64_e32 v[148:149], 0x5ff
	s_movk_i32 s60, 0xc1
	v_add_u32_e32 v157, s61, v154
	v_add_u32_e32 v158, s62, v154
	v_add_u32_e32 v159, 0, v2
	s_mov_b32 s1, 0
	s_mov_b32 s63, 0
	s_barrier
	s_branch .LBB0_1823

.LBB0_1989:
	s_waitcnt vmcnt(0)
	v_lshrrev_b32_e32 v2, 1, v128
	v_lshrrev_b32_e32 v3, 5, v128
	v_and_b32_e32 v2, 24, v2
	v_and_b32_e32 v3, 4, v3
	v_bfe_u32 v4, v128, 2, 2
	v_lshlrev_b32_e32 v0, 4, v128
	s_waitcnt lgkmcnt(0)
	v_and_b32_e32 v1, 32, v128
	v_bfe_u32 v10, v128, 2, 4
	v_or3_b32 v2, v3, v4, v2
	v_lshrrev_b32_e32 v3, 3, v128
	s_movk_i32 s1, 0x70
	v_bitop3_b32 v8, v0, v1, 48 bitop3:0x6c
	v_and_b32_e32 v9, 64, v128
	v_and_or_b32 v4, v3, s1, v10
	s_movk_i32 s1, 0x60
	v_add_u32_e32 v11, 0x2000, v0
	v_or_b32_e32 v1, v8, v9
	v_and_or_b32 v3, v3, s1, v2
	v_lshrrev_b32_e32 v0, 7, v11
	s_movk_i32 s1, 0xf0
	s_add_u32 s3, s70, 0x5080000
	v_lshl_or_b32 v132, v3, 11, v1
	v_and_or_b32 v3, v0, s1, v10
	s_movk_i32 s1, 0xe0
	s_addc_u32 s44, s71, 0
	s_lshr_b32 s5, s6, 6
	v_and_or_b32 v0, v0, s1, v2
	s_ashr_i32 s37, s36, 31
	s_ashr_i32 s1, s0, 31
	s_lshr_b32 s4, s6, 8
	s_lshl_b32 s45, s5, 10
	s_lshl_b64 s[8:9], s[36:37], 19
	s_lshl_b64 s[10:11], s[0:1], 19
	s_add_u32 s40, s3, s10
	s_addc_u32 s41, s44, s11
	s_add_i32 s46, s45, 0
	s_add_i32 m0, s46, 0x10000
	v_lshl_or_b32 v136, v0, 11, v1
	global_load_lds_dwordx4 v132, s[40:41]
	s_add_i32 m0, s46, 0x12000
	s_add_u32 s10, s40, 0x40000
	global_load_lds_dwordx4 v136, s[40:41]
	s_addc_u32 s11, s41, 0
	s_add_i32 m0, s46, 0x14000
	v_lshl_or_b32 v130, v4, 11, v1
	global_load_lds_dwordx4 v132, s[10:11]
	s_add_i32 m0, s46, 0x16000
	s_add_u32 s38, s20, s8
	s_addc_u32 s39, s21, s9
	s_add_i32 s47, s46, 0x2000
	global_load_lds_dwordx4 v136, s[10:11]
	s_mov_b32 m0, s46
	s_add_u32 s8, s38, 0x40000
	v_lshl_or_b32 v134, v3, 11, v1
	global_load_lds_dwordx4 v130, s[38:39]
	s_mov_b32 m0, s47
	s_addc_u32 s9, s39, 0
	s_add_i32 s48, s46, 0x4000
	global_load_lds_dwordx4 v134, s[38:39]
	s_mov_b32 m0, s48
	s_add_i32 s49, s46, 0x6000
	global_load_lds_dwordx4 v130, s[8:9]
	s_mov_b32 m0, s49
	v_mov_b32_e32 v133, 0
	global_load_lds_dwordx4 v134, s[8:9]
	v_mov_b32_e32 v137, v133
	v_mov_b32_e32 v131, v133
	v_mov_b32_e32 v135, v133
	s_cmp_eq_u32 s4, 1
	s_mov_b32 s1, 0
	v_lshl_add_u64 v[6:7], s[40:41], 0, v[132:133]
	v_lshl_add_u64 v[4:5], s[40:41], 0, v[136:137]
	v_lshl_add_u64 v[0:1], s[38:39], 0, v[130:131]
	s_cselect_b64 s[8:9], -1, 0
	v_lshl_add_u64 v[2:3], s[38:39], 0, v[134:135]
	s_mov_b64 s[10:11], 0x80
	s_and_b32 s50, s5, 3
	s_add_i32 m0, s46, 0x18000
	v_lshl_add_u64 v[6:7], v[6:7], 0, s[10:11]
	s_lshl_b32 s5, s4, 13
	s_lshl_b32 s7, s50, 12
	global_load_lds_dwordx4 v[6:7], off
	v_lshl_add_u64 v[4:5], v[4:5], 0, s[10:11]
	s_add_i32 m0, s46, 0x1a000
	s_add_i32 s51, s46, 0x8000
	s_add_i32 s52, s46, 0xa000
	global_load_lds_dwordx4 v[4:5], off
	v_lshl_add_u64 v[0:1], v[0:1], 0, s[10:11]
	s_mov_b32 m0, s51
	s_add_u32 s12, s40, 0x40080
	global_load_lds_dwordx4 v[0:1], off
	v_lshl_add_u64 v[0:1], v[2:3], 0, s[10:11]
	s_mov_b32 m0, s52
	s_addc_u32 s13, s41, 0
	global_load_lds_dwordx4 v[0:1], off
	s_add_i32 m0, s46, 0x1c000
	v_lshl_add_u64 v[0:1], s[12:13], 0, v[132:133]
	global_load_lds_dwordx4 v[0:1], off
	v_lshl_add_u64 v[0:1], s[12:13], 0, v[136:137]
	s_add_i32 m0, s46, 0x1e000
	v_lshlrev_b32_e32 v4, 2, v128
	global_load_lds_dwordx4 v[0:1], off
	s_cmp_lg_u32 s4, 1
	s_cbranch_scc1 .LBB0_1991
	s_barrier
.LBB0_1991:
	s_waitcnt vmcnt(8)
	s_barrier
	v_bfe_u32 v0, v128, 4, 2
	v_and_b32_e32 v1, 15, v128
	v_lshlrev_b32_e32 v3, 4, v0
	v_lshl_or_b32 v150, s4, 6, v1
	v_lshl_or_b32 v1, v1, 6, v3
	v_and_b32_e32 v4, 32, v4
	v_lshlrev_b32_e32 v5, 6, v128
	s_movk_i32 s4, 0x3c0
	v_lshlrev_b32_e32 v2, 3, v0
	v_bitop3_b32 v1, v1, s5, v4 bitop3:0xde
	v_and_or_b32 v3, v5, s4, v3
	v_cmp_eq_u32_e64 s[4:5], 0, v0
	v_lshlrev_b32_e32 v0, 8, v128
	v_lshl_or_b32 v152, s50, 5, v2
	v_and_b32_e32 v0, 0x38000, v0
	v_lshlrev_b32_e32 v2, 11, v10
	v_or3_b32 v0, v8, v0, v2
	v_add_u32_e32 v138, v0, v9
	v_lshlrev_b32_e32 v0, 4, v11
	v_and_b32_e32 v0, 0x78000, v0
	s_waitcnt vmcnt(6)
	s_cmpk_lt_u32 s6, 0x100
	v_or3_b32 v0, v8, v0, v2
	v_bitop3_b32 v151, s7, v3, v4 bitop3:0xf6
	s_cselect_b64 s[22:23], -1, 0
	v_add_u32_e32 v140, v0, v9
	s_add_i32 s56, 0, 0x10000
	s_add_i32 s57, 0, 0x14000
	v_mbcnt_lo_u32_b32 v0, -1, 0
	s_ashr_i32 s53, s72, 31
	s_mov_b32 s54, s72
	s_ashr_i32 s55, s2, 31
	v_mov_b32_e32 v139, v133
	v_mov_b32_e32 v141, v133
	v_mov_b64_e32 v[142:143], 0x200
	v_mov_b64_e32 v[144:145], 0x1ff
	v_add_u32_e32 v153, s56, v151
	v_add_u32_e32 v154, s57, v151
	v_add_u32_e32 v155, 0, v1
	v_mbcnt_hi_u32_b32 v156, -1, v0
	s_mov_b32 s58, 0
	s_barrier
	s_branch .LBB0_1994

.LBB0_2082:
	s_or_b64 exec, exec, s[0:1]
	s_cmpk_gt_i32 s2, 0xaff
	v_readfirstlane_b32 s5, v128
	s_waitcnt lgkmcnt(0)
	s_barrier
	s_cbranch_scc1 .LBB0_2098
	v_lshrrev_b32_e32 v0, 5, v128
	v_lshrrev_b32_e32 v2, 1, v128
	v_and_b32_e32 v0, 4, v0
	v_bfe_u32 v1, v128, 2, 2
	v_and_b32_e32 v12, 24, v2
	v_or3_b32 v0, v0, v1, v12
	v_lshlrev_b32_e32 v1, 4, v128
	v_add_u32_e32 v9, 0x2000, v1
	v_lshrrev_b32_e32 v2, 7, v9
	s_movk_i32 s0, 0xe0
	v_and_b32_e32 v4, 32, v128
	v_and_or_b32 v3, v2, s0, v0
	v_bitop3_b32 v10, v1, v4, 48 bitop3:0x6c
	v_and_b32_e32 v11, 64, v128
	v_bfe_u32 v13, v128, 2, 4
	s_movk_i32 s0, 0xf0
	s_lshr_b32 s6, s5, 6
	v_or_b32_e32 v1, v10, v11
	v_and_or_b32 v2, v2, s0, v13
	s_lshr_b32 s10, s5, 8
	s_lshl_b32 s38, s6, 10
	v_lshl_or_b32 v132, v2, 11, v1
	v_lshrrev_b32_e32 v2, 3, v128
	s_movk_i32 s0, 0x60
	s_add_u32 s39, s70, 0x5280000
	v_and_or_b32 v0, v2, s0, v0
	s_movk_i32 s0, 0x70
	s_addc_u32 s40, s71, 0
	v_lshl_or_b32 v134, v0, 11, v1
	v_and_or_b32 v0, v2, s0, v13
	s_lshr_b32 s0, s3, 29
	s_add_i32 s0, s2, s0
	s_ashr_i32 s1, s0, 3
	s_and_b32 s0, s0, -8
	s_sub_i32 s0, s2, s0
	s_cmp_lt_i32 s0, 0
	s_movk_i32 s41, 0x161
	s_cselect_b32 s4, s41, 0x160
	s_mul_i32 s0, s0, s4
	s_add_i32 s0, s0, s1
	s_mul_hi_i32 s1, s0, 0x2e8ba2e9
	s_lshr_b32 s4, s1, 31
	s_ashr_i32 s1, s1, 5
	s_add_i32 s1, s1, s4
	s_lshl_b32 s7, s1, 3
	s_mulk_i32 s1, 0xb0
	s_sub_i32 s0, s0, s1
	s_bfe_u32 s1, s0, 0x3001c
	s_add_i32 s1, s0, s1
	s_sext_i32_i16 s4, s1
	s_and_b32 s1, s1, 0xfff8
	s_sub_i32 s0, s0, s1
	s_sext_i32_i16 s0, s0
	s_lshr_b32 s4, s4, 3
	s_add_i32 s24, s7, s0
	s_ashr_i32 s25, s24, 31
	s_bfe_i64 s[8:9], s[4:5], 0x100000
	s_lshl_b64 s[0:1], s[24:25], 19
	s_lshl_b64 s[8:9], s[8:9], 19
	s_add_u32 s28, s39, s8
	s_addc_u32 s29, s40, s9
	s_add_i32 s25, s38, 0
	s_add_i32 m0, s25, 0x10000
	v_lshl_or_b32 v130, v3, 11, v1
	global_load_lds_dwordx4 v134, s[28:29]
	s_add_i32 m0, s25, 0x12000
	s_add_u32 s8, s28, 0x40000
	global_load_lds_dwordx4 v130, s[28:29]
	s_addc_u32 s9, s29, 0
	s_add_i32 m0, s25, 0x14000
	v_lshl_or_b32 v136, v0, 11, v1
	global_load_lds_dwordx4 v134, s[8:9]
	s_add_i32 m0, s25, 0x16000
	s_add_u32 s26, s14, s0
	s_addc_u32 s27, s15, s1
	s_add_i32 s42, s25, 0x2000
	global_load_lds_dwordx4 v130, s[8:9]
	s_mov_b32 m0, s25
	s_add_u32 s0, s26, 0x40000
	global_load_lds_dwordx4 v136, s[26:27]
	s_mov_b32 m0, s42
	s_addc_u32 s1, s27, 0
	s_add_i32 s43, s25, 0x4000
	global_load_lds_dwordx4 v132, s[26:27]
	s_mov_b32 m0, s43
	s_add_i32 s44, s25, 0x6000
	global_load_lds_dwordx4 v136, s[0:1]
	s_mov_b32 m0, s44
	v_mov_b32_e32 v135, 0
	global_load_lds_dwordx4 v132, s[0:1]
	v_mov_b32_e32 v131, v135
	v_mov_b32_e32 v137, v135
	v_mov_b32_e32 v133, v135
	s_cmp_eq_u32 s10, 1
	s_mov_b32 s12, 0
	v_lshl_add_u64 v[6:7], s[28:29], 0, v[134:135]
	v_lshl_add_u64 v[4:5], s[28:29], 0, v[130:131]
	v_lshl_add_u64 v[0:1], s[26:27], 0, v[136:137]
	s_cselect_b64 s[0:1], -1, 0
	v_lshl_add_u64 v[2:3], s[26:27], 0, v[132:133]
	s_lshl_b32 s6, s6, 5
	s_and_b32 s18, s6, 0x60
	s_mov_b64 s[6:7], 0x80
	s_add_i32 m0, s25, 0x18000
	v_lshl_add_u64 v[6:7], v[6:7], 0, s[6:7]
	s_lshl_b32 s11, s10, 13
	s_lshl_b32 s19, s18, 7
	global_load_lds_dwordx4 v[6:7], off
	v_lshl_add_u64 v[4:5], v[4:5], 0, s[6:7]
	s_add_i32 m0, s25, 0x1a000
	s_add_i32 s45, s25, 0x8000
	s_add_i32 s46, s25, 0xa000
	global_load_lds_dwordx4 v[4:5], off
	v_lshl_add_u64 v[0:1], v[0:1], 0, s[6:7]
	s_mov_b32 m0, s45
	s_add_u32 s8, s28, 0x40080
	global_load_lds_dwordx4 v[0:1], off
	v_lshl_add_u64 v[0:1], v[2:3], 0, s[6:7]
	s_mov_b32 m0, s46
	s_addc_u32 s9, s29, 0
	global_load_lds_dwordx4 v[0:1], off
	s_add_i32 m0, s25, 0x1c000
	v_lshl_add_u64 v[0:1], s[8:9], 0, v[134:135]
	global_load_lds_dwordx4 v[0:1], off
	v_lshl_add_u64 v[0:1], s[8:9], 0, v[130:131]
	s_add_i32 m0, s25, 0x1e000
	s_sext_i32_i16 s13, s4
	global_load_lds_dwordx4 v[0:1], off
	s_cmp_lg_u32 s10, 1
	s_cbranch_scc1 .LBB0_2085
	s_barrier
.LBB0_2085:
	s_waitcnt vmcnt(8)
	s_barrier
	v_and_b32_e32 v0, 15, v128
	v_lshlrev_b32_e32 v1, 1, v12
	v_lshl_or_b32 v129, s10, 6, v0
	v_lshl_or_b32 v2, v0, 6, v1
	v_lshlrev_b32_e32 v0, 2, v0
	v_and_b32_e32 v3, 32, v0
	v_bitop3_b32 v2, v2, s11, v3 bitop3:0xde
	v_lshlrev_b32_e32 v3, 6, v128
	s_movk_i32 s4, 0x3c0
	s_cmpk_lt_u32 s5, 0x100
	v_and_or_b32 v1, v3, s4, v1
	s_cselect_b64 s[8:9], -1, 0
	s_lshl_b32 s4, s10, 8
	s_add_i32 s4, s4, 0
	s_add_i32 s4, s4, 0x20000
	v_and_b32_e32 v3, 32, v8
	v_add_u32_e32 v151, s4, v0
	v_lshlrev_b32_e32 v0, 8, v128
	v_bitop3_b32 v150, s19, v1, v3 bitop3:0xf6
	v_and_b32_e32 v0, 0x38000, v0
	v_lshlrev_b32_e32 v1, 11, v13
	v_or3_b32 v0, v10, v0, v1
	v_add_u32_e32 v138, v0, v11
	v_lshlrev_b32_e32 v0, 4, v9
	s_waitcnt vmcnt(6)
	v_and_b32_e32 v0, 0x78000, v0
	v_or3_b32 v0, v10, v0, v1
	s_add_i32 s47, 0, 0x10000
	s_add_i32 s48, 0, 0x14000
	v_or_b32_e32 v152, s18, v12
	v_mov_b32_e32 v139, v135
	v_add_u32_e32 v140, v0, v11
	v_mov_b32_e32 v141, v135
	v_mov_b64_e32 v[142:143], 0xb00
	v_mov_b64_e32 v[144:145], 0xaff
	v_add_u32_e32 v153, s47, v150
	v_add_u32_e32 v154, s48, v150
	v_add_u32_e32 v155, 0, v2
	s_movk_i32 s49, 0x1600
	s_mov_b32 s50, 0
	s_barrier
	s_branch .LBB0_2088

.LBB0_2158:
	s_add_u32 s38, s70, 0x5d80000
	s_addc_u32 s39, s71, 0
	s_add_i32 s1, s6, s1
	s_ashr_i32 s6, s1, 31
	s_lshr_b32 s6, s6, 27
	s_add_i32 s6, s1, s6
	s_ashr_i32 s7, s6, 5
	s_and_b32 s6, s6, 0xffe0
	s_waitcnt vmcnt(0)
	v_lshrrev_b32_e32 v3, 1, v128
	s_sub_i32 s6, s1, s6
	v_and_b32_e32 v10, 24, v3
	v_lshrrev_b32_e32 v3, 5, v128
	s_bfe_i32 s1, s6, 0x80000
	v_and_b32_e32 v3, 4, v3
	v_bfe_u32 v4, v128, 2, 2
	s_bfe_u32 s1, s1, 0x3000c
	v_lshlrev_b32_e32 v0, 4, v128
	s_waitcnt lgkmcnt(0)
	v_and_b32_e32 v1, 32, v128
	v_bfe_u32 v2, v128, 2, 4
	v_or3_b32 v3, v3, v4, v10
	v_lshrrev_b32_e32 v4, 3, v128
	s_movk_i32 s5, 0x70
	s_add_i32 s8, s6, s1
	v_bitop3_b32 v8, v0, v1, 48 bitop3:0x6c
	v_and_or_b32 v5, v4, s5, v2
	s_movk_i32 s5, 0x60
	v_add_u32_e32 v0, 0x2000, v0
	s_bfe_i32 s1, s8, 0x80000
	s_and_b32 s8, s8, 0xf8
	v_and_or_b32 v4, v4, s5, v3
	v_lshrrev_b32_e32 v0, 7, v0
	s_movk_i32 s5, 0xf0
	s_sub_i32 s6, s6, s8
	v_and_or_b32 v2, v0, s5, v2
	s_movk_i32 s5, 0xe0
	s_lshl_b32 s7, s7, 3
	s_sext_i32_i16 s9, s1
	s_sext_i32_i8 s6, s6
	v_and_b32_e32 v9, 64, v128
	v_and_or_b32 v0, v0, s5, v3
	s_lshr_b32 s5, s4, 6
	s_add_i32 s12, s7, s6
	s_ashr_i32 s6, s9, 3
	s_lshr_b32 s0, s4, 8
	v_or_b32_e32 v1, v8, v9
	s_lshl_b32 s40, s5, 10
	s_lshr_b32 s1, s9, 3
	s_mul_hi_i32 s7, s6, 0x160000
	s_mul_i32 s6, s6, 0x160000
	v_lshrrev_b32_e32 v1, 1, v1
	v_mul_u32_u24_e32 v4, 0xb00, v4
	s_add_u32 s30, s38, s6
	v_or_b32_e32 v4, v4, v1
	s_addc_u32 s31, s39, s7
	s_add_i32 s41, s40, 0
	v_lshlrev_b32_e32 v132, 1, v4
	v_mul_u32_u24_e32 v0, 0xb00, v0
	s_add_i32 m0, s41, 0x10000
	v_or_b32_e32 v0, v0, v1
	global_load_lds_dwordx4 v132, s[30:31]
	s_add_i32 m0, s41, 0x12000
	v_lshlrev_b32_e32 v136, 1, v0
	s_add_u32 s6, s30, 0xb0000
	global_load_lds_dwordx4 v136, s[30:31]
	s_addc_u32 s7, s31, 0
	s_add_i32 m0, s41, 0x14000
	s_mul_i32 s10, s12, 0x160000
	global_load_lds_dwordx4 v132, s[6:7]
	s_add_i32 m0, s41, 0x16000
	v_mul_u32_u24_e32 v11, 0xb00, v5
	s_mul_hi_i32 s8, s12, 0x160000
	s_add_u32 s28, s16, s10
	v_or_b32_e32 v5, v1, v11
	v_mul_u32_u24_e32 v12, 0xb00, v2
	s_addc_u32 s29, s17, s8
	s_add_i32 s42, s41, 0x2000
	v_lshlrev_b32_e32 v130, 1, v5
	v_or_b32_e32 v2, v12, v1
	global_load_lds_dwordx4 v136, s[6:7]
	s_mov_b32 m0, s41
	s_add_u32 s6, s28, 0xb0000
	v_lshlrev_b32_e32 v134, 1, v2
	global_load_lds_dwordx4 v130, s[28:29]
	s_mov_b32 m0, s42
	s_addc_u32 s7, s29, 0
	s_add_i32 s43, s41, 0x4000
	global_load_lds_dwordx4 v134, s[28:29]
	s_mov_b32 m0, s43
	s_add_i32 s44, s41, 0x6000
	global_load_lds_dwordx4 v130, s[6:7]
	s_mov_b32 m0, s44
	v_mov_b32_e32 v133, 0
	global_load_lds_dwordx4 v134, s[6:7]
	v_mov_b32_e32 v137, v133
	v_mov_b32_e32 v131, v133
	v_mov_b32_e32 v135, v133
	s_cmp_eq_u32 s0, 1
	s_mov_b32 s45, 0
	v_lshl_add_u64 v[6:7], s[30:31], 0, v[132:133]
	v_lshl_add_u64 v[4:5], s[30:31], 0, v[136:137]
	v_lshl_add_u64 v[0:1], s[28:29], 0, v[130:131]
	s_cselect_b64 s[6:7], -1, 0
	v_lshl_add_u64 v[2:3], s[28:29], 0, v[134:135]
	s_lshl_b32 s5, s5, 5
	s_mov_b64 s[8:9], 0x80
	s_and_b32 s5, s5, 0x60
	s_add_i32 m0, s41, 0x18000
	v_lshl_add_u64 v[6:7], v[6:7], 0, s[8:9]
	s_lshl_b32 s18, s0, 13
	s_lshl_b32 s19, s5, 7
	global_load_lds_dwordx4 v[6:7], off
	v_lshl_add_u64 v[4:5], v[4:5], 0, s[8:9]
	s_add_i32 m0, s41, 0x1a000
	s_add_i32 s46, s41, 0x8000
	s_add_i32 s47, s41, 0xa000
	global_load_lds_dwordx4 v[4:5], off
	v_lshl_add_u64 v[0:1], v[0:1], 0, s[8:9]
	s_mov_b32 m0, s46
	s_add_u32 s10, s30, 0xb0080
	global_load_lds_dwordx4 v[0:1], off
	v_lshl_add_u64 v[0:1], v[2:3], 0, s[8:9]
	s_mov_b32 m0, s47
	s_addc_u32 s11, s31, 0
	global_load_lds_dwordx4 v[0:1], off
	s_add_i32 m0, s41, 0x1c000
	v_lshl_add_u64 v[0:1], s[10:11], 0, v[132:133]
	global_load_lds_dwordx4 v[0:1], off
	v_lshl_add_u64 v[0:1], s[10:11], 0, v[136:137]
	s_add_i32 m0, s41, 0x1e000
	v_lshlrev_b32_e32 v2, 2, v128
	global_load_lds_dwordx4 v[0:1], off
	s_cmp_lg_u32 s0, 1
	s_cbranch_scc1 .LBB0_2160
	s_barrier
.LBB0_2160:
	s_waitcnt vmcnt(8)
	s_barrier
	v_and_b32_e32 v0, 15, v128
	v_lshl_or_b32 v150, s0, 6, v0
	v_lshlrev_b32_e32 v1, 1, v10
	v_lshlrev_b32_e32 v3, 6, v128
	s_movk_i32 s0, 0x3c0
	v_lshl_or_b32 v0, v0, 6, v1
	v_and_b32_e32 v2, 32, v2
	v_and_or_b32 v1, v3, s0, v1
	v_bitop3_b32 v151, s19, v1, v2 bitop3:0xf6
	s_waitcnt vmcnt(6)
	s_cmpk_lt_u32 s4, 0x100
	v_add_u16_e32 v1, v8, v9
	v_bitop3_b32 v0, v0, s18, v2 bitop3:0xde
	s_cselect_b64 s[10:11], -1, 0
	v_lshrrev_b16_e32 v1, 1, v1
	s_add_i32 s50, 0, 0x10000
	s_add_i32 s51, 0, 0x14000
	s_sext_i32_i8 s13, s1
	s_ashr_i32 s48, s72, 31
	s_mov_b32 s49, s72
	v_or_b32_e32 v152, s5, v10
	v_add_lshl_u32 v128, v11, v1, 1
	v_mov_b32_e32 v129, v133
	v_add_lshl_u32 v138, v12, v1, 1
	v_mov_b32_e32 v139, v133
	v_mov_b64_e32 v[140:141], 0x200
	v_mov_b64_e32 v[142:143], 0x1ff
	v_add_u32_e32 v153, s50, v151
	v_add_u32_e32 v154, s51, v151
	v_add_u32_e32 v155, 0, v0
	s_mov_b64 s[18:19], 0x20000
	s_mov_b64 s[20:21], 0x24000
	s_mov_b64 s[22:23], 0x28000
	s_mov_b64 s[24:25], 0x2c000
	s_barrier
	s_branch .LBB0_2163
